# v35 + DYN GEMM K-loop: per-iteration publish test (v_or+v_cmp+saveexec right after the barrier) skipped by a scalar t!=0 test (shorten wave-uniform branch test)
# speedup vs baseline: 1.0005x; 1.0005x over previous
; #define PG8_STAGE(bufoff, gbase, voff) do { _Pragma("unroll") for (int _i = 0; _i < 2; ++_i) \
;         __builtin_amdgcn_global_load_lds((const unsigned*)((const char*)(gbase) + (voff)[_i]), (LAS unsigned*)(lds + (bufoff) + ldsw + _i * 8192), 16, 0, 0); } while (0)
; #define PG8_LDA(dst, b, h) do { _Pragma("unroll") for (int m = 0; m < 4; ++m) _Pragma("unroll") for (int k = 0; k < 2; ++k) dst[m][k] = *(const LAS bf16x8*)(lds + PG8_SA(b, h) + aoff + m * 2048 + k * 1024); } while (0)
; #define PG8_LDB(dst, b, h) do { _Pragma("unroll") for (int n = 0; n < 2; ++n) _Pragma("unroll") for (int k = 0; k < 2; ++k) dst[n][k] = *(const LAS bf16x8*)(lds + PG8_SB(b, h) + boff + n * 2048 + k * 1024); } while (0)
; #define PG8_MMA(ai, bj, At, Bt) do { __builtin_amdgcn_s_setprio(1); _Pragma("unroll") for (int m = 0; m < 4; ++m) _Pragma("unroll") for (int n = 0; n < 2; ++n) _Pragma("unroll") for (int k = 0; k < 2; ++k) \
;         acc[ai][bj][m][n] = __builtin_amdgcn_mfma_f32_16x16x32_bf16(Bt[n][k], At[m][k], acc[ai][bj][m][n], 0, 0, 0); __builtin_amdgcn_s_setprio(0); } while (0)
; template <class Epi, bool DYN = false>
; __device__ __forceinline__ void gemm_phase(LAS unsigned char* lds, const Gemm g, const Epi& E, int wave, unsigned* ctr = nullptr) {
;     ...
;         for (int t = 0; t < nt; t += 2) {
;             const bool last = (t == nt - 2);
;             if (DYN && last) { const int nw = __builtin_amdgcn_readfirstlane(slot[(ui + 1) & 1]); has_next = nw >= 0;
;                 if (has_next) { decode(nw, nxt); nA = (const char*)g.A + (size_t)nxt.pm * tstepA; nB = (const char*)g.Bt + (size_t)nxt.pn * tstepB; } }
;             const char* a1 = cA + (size_t)(t + 1) * kstepA;
;             const char* a2 = last ? nA : cA + (size_t)(t + 2) * kstepA; const char* b2 = last ? nB : cB + (size_t)(t + 2) * kstepB;
;             const char* a3 = a2 + kstepA; const char* b3 = b2 + kstepB;
;             PG8_LDB(B0, 0, 0); PG8_SCHED; PG8_LDA(At, 0, 0); PG8_STAGE(PG8_SA(1, 1), a1 + hstepA, voffA);
;             PG8_WAIT_L(8); PG8_BAR; PG8_WAIT_L(0); PG8_MMA(0, 0, At, B0); PG8_BAR; PG8_SCHED;
;             PG8_LDB(B1, 0, 1); PG8_STAGE(PG8_SB(0, 0), b2, voffB);
;             PG8_BAR; PG8_WAIT_L(0); PG8_MMA(0, 1, At, B1); PG8_BAR;
;             PG8_LDA(At, 0, 1); PG8_STAGE(PG8_SA(0, 0), a2, voffA);
;             PG8_BAR; PG8_WAIT_L(0); PG8_MMA(1, 0, At, B0); PG8_BAR; PG8_SCHED;
.LBB0_86:
	s_add_i32 s8, s8, 2
	s_add_u32 s9, s68, s72
	s_addc_u32 s10, s69, s73
	s_and_b64 s[0:1], s[38:39], exec
	s_cselect_b32 s75, s79, s10
	s_cselect_b32 s74, s78, s9
	s_add_i32 s9, 0, 0x10000
	v_add_u32_e32 v142, s9, v200
	ds_read_b128 v[130:133], v142
	ds_read_b128 v[134:137], v142 offset:1024
	ds_read_b128 v[138:141], v142 offset:2048
	ds_read_b128 v[142:145], v142 offset:3072
	s_and_b64 s[0:1], s[38:39], exec
	s_cselect_b32 s71, s65, s7
	s_cselect_b32 s70, s64, s6
	v_lshl_add_u64 v[196:197], s[68:69], 0, v[188:189]
	s_add_i32 m0, s18, 0xc000
	ds_read_b128 v[146:149], v202
	ds_read_b128 v[150:153], v202 offset:1024
	ds_read_b128 v[154:157], v202 offset:2048
	ds_read_b128 v[158:161], v202 offset:3072
	ds_read_b128 v[162:165], v202 offset:4096
	ds_read_b128 v[166:169], v202 offset:5120
	ds_read_b128 v[170:173], v202 offset:6144
	ds_read_b128 v[174:177], v202 offset:7168
	global_load_lds_dwordx4 v[196:197], off
	v_lshl_add_u64 v[196:197], s[68:69], 0, v[190:191]
	s_add_i32 m0, s18, 0xe000
	s_nop 0
	global_load_lds_dwordx4 v[196:197], off
	s_waitcnt lgkmcnt(8)
	s_barrier
	s_waitcnt lgkmcnt(0)
	s_setprio 1
	s_waitcnt lgkmcnt(0)
	v_mfma_f32_16x16x32_bf16 v[126:129], v[130:133], v[146:149], v[126:129]
	v_mfma_f32_16x16x32_bf16 v[122:125], v[138:141], v[146:149], v[122:125]
	v_mfma_f32_16x16x32_bf16 v[118:121], v[130:133], v[154:157], v[118:121]
	v_mfma_f32_16x16x32_bf16 v[114:117], v[138:141], v[154:157], v[114:117]
	v_mfma_f32_16x16x32_bf16 v[110:113], v[130:133], v[162:165], v[110:113]
	v_mfma_f32_16x16x32_bf16 v[106:109], v[138:141], v[162:165], v[106:109]
	v_mfma_f32_16x16x32_bf16 v[102:105], v[130:133], v[170:173], v[102:105]
	v_mfma_f32_16x16x32_bf16 v[94:97], v[138:141], v[170:173], v[94:97]
	v_mfma_f32_16x16x32_bf16 v[126:129], v[134:137], v[150:153], v[126:129]
	v_mfma_f32_16x16x32_bf16 v[122:125], v[142:145], v[150:153], v[122:125]
	v_mfma_f32_16x16x32_bf16 v[118:121], v[134:137], v[158:161], v[118:121]
	v_mfma_f32_16x16x32_bf16 v[114:117], v[142:145], v[158:161], v[114:117]
	v_mfma_f32_16x16x32_bf16 v[110:113], v[134:137], v[166:169], v[110:113]
	v_mfma_f32_16x16x32_bf16 v[106:109], v[142:145], v[166:169], v[106:109]
	v_mfma_f32_16x16x32_bf16 v[102:105], v[134:137], v[174:177], v[102:105]
	v_mfma_f32_16x16x32_bf16 v[94:97], v[142:145], v[174:177], v[94:97]
	s_setprio 0
	s_barrier
	s_add_i32 s10, 0, 0x14000
	s_add_i32 s0, s9, s17
	v_add_u32_e32 v212, s10, v200
	v_lshl_add_u64 v[216:217], s[70:71], 0, v[178:179]
	s_mov_b32 m0, s0
	ds_read_b128 v[196:199], v212
	ds_read_b128 v[204:207], v212 offset:1024
	ds_read_b128 v[208:211], v212 offset:2048
	ds_read_b128 v[212:215], v212 offset:3072
	global_load_lds_dwordx4 v[216:217], off
	v_lshl_add_u64 v[216:217], s[70:71], 0, v[182:183]
	s_add_i32 m0, s0, 0x2000
	s_nop 0
	global_load_lds_dwordx4 v[216:217], off
	s_barrier
	s_waitcnt lgkmcnt(0)
	s_setprio 1
	s_waitcnt lgkmcnt(0)
	v_mfma_f32_16x16x32_bf16 v[86:89], v[196:199], v[146:149], v[86:89]
	v_mfma_f32_16x16x32_bf16 v[78:81], v[208:211], v[146:149], v[78:81]
	v_mfma_f32_16x16x32_bf16 v[70:73], v[196:199], v[154:157], v[70:73]
	v_mfma_f32_16x16x32_bf16 v[62:65], v[208:211], v[154:157], v[62:65]
	v_mfma_f32_16x16x32_bf16 v[54:57], v[196:199], v[162:165], v[54:57]
	v_mfma_f32_16x16x32_bf16 v[46:49], v[208:211], v[162:165], v[46:49]
	v_mfma_f32_16x16x32_bf16 v[42:45], v[196:199], v[170:173], v[42:45]
	v_mfma_f32_16x16x32_bf16 v[38:41], v[208:211], v[170:173], v[38:41]
	v_mfma_f32_16x16x32_bf16 v[86:89], v[204:207], v[150:153], v[86:89]
	v_mfma_f32_16x16x32_bf16 v[78:81], v[212:215], v[150:153], v[78:81]
	v_mfma_f32_16x16x32_bf16 v[70:73], v[204:207], v[158:161], v[70:73]
	v_mfma_f32_16x16x32_bf16 v[62:65], v[212:215], v[158:161], v[62:65]
	v_mfma_f32_16x16x32_bf16 v[54:57], v[204:207], v[166:169], v[54:57]
	v_mfma_f32_16x16x32_bf16 v[46:49], v[212:215], v[166:169], v[46:49]
	v_mfma_f32_16x16x32_bf16 v[42:45], v[204:207], v[174:177], v[42:45]
	v_mfma_f32_16x16x32_bf16 v[38:41], v[212:215], v[174:177], v[38:41]
	s_setprio 0
	s_mov_b32 m0, s18
	v_lshl_add_u64 v[216:217], s[74:75], 0, v[0:1]
	s_barrier
	ds_read_b128 v[146:149], v202 offset:16384
	ds_read_b128 v[150:153], v202 offset:17408
	ds_read_b128 v[154:157], v202 offset:18432
	ds_read_b128 v[158:161], v202 offset:19456
	ds_read_b128 v[162:165], v202 offset:20480
	ds_read_b128 v[166:169], v202 offset:21504
	ds_read_b128 v[170:173], v202 offset:22528
	ds_read_b128 v[174:177], v202 offset:23552
	global_load_lds_dwordx4 v[216:217], off
	v_lshl_add_u64 v[218:219], s[74:75], 0, v[180:181]
	s_mov_b32 m0, s19
	s_nop 0
	global_load_lds_dwordx4 v[218:219], off
	s_barrier
	s_waitcnt lgkmcnt(0)
	s_setprio 1
	s_waitcnt lgkmcnt(0)
	v_mfma_f32_16x16x32_bf16 v[34:37], v[130:133], v[146:149], v[34:37]
	v_mfma_f32_16x16x32_bf16 v[26:29], v[138:141], v[146:149], v[26:29]
	v_mfma_f32_16x16x32_bf16 v[22:25], v[130:133], v[154:157], v[22:25]
	v_mfma_f32_16x16x32_bf16 v[18:21], v[138:141], v[154:157], v[18:21]
	v_mfma_f32_16x16x32_bf16 v[14:17], v[130:133], v[162:165], v[14:17]
	v_mfma_f32_16x16x32_bf16 v[10:13], v[138:141], v[162:165], v[10:13]
	v_mfma_f32_16x16x32_bf16 v[6:9], v[130:133], v[170:173], v[6:9]
	v_mfma_f32_16x16x32_bf16 v[2:5], v[138:141], v[170:173], v[2:5]
	v_mfma_f32_16x16x32_bf16 v[34:37], v[134:137], v[150:153], v[34:37]
	v_mfma_f32_16x16x32_bf16 v[26:29], v[142:145], v[150:153], v[26:29]
	v_mfma_f32_16x16x32_bf16 v[22:25], v[134:137], v[158:161], v[22:25]
	v_mfma_f32_16x16x32_bf16 v[18:21], v[142:145], v[158:161], v[18:21]
	v_mfma_f32_16x16x32_bf16 v[14:17], v[134:137], v[166:169], v[14:17]
	v_mfma_f32_16x16x32_bf16 v[10:13], v[142:145], v[166:169], v[10:13]
	v_mfma_f32_16x16x32_bf16 v[6:9], v[134:137], v[174:177], v[6:9]
	v_mfma_f32_16x16x32_bf16 v[2:5], v[142:145], v[174:177], v[2:5]
	s_setprio 0
	s_barrier
; #define PG8_STAGE(bufoff, gbase, voff) do { _Pragma("unroll") for (int _i = 0; _i < 2; ++_i) \
;         __builtin_amdgcn_global_load_lds((const unsigned*)((const char*)(gbase) + (voff)[_i]), (LAS unsigned*)(lds + (bufoff) + ldsw + _i * 8192), 16, 0, 0); } while (0)
; #define PG8_LDA(dst, b, h) do { _Pragma("unroll") for (int m = 0; m < 4; ++m) _Pragma("unroll") for (int k = 0; k < 2; ++k) dst[m][k] = *(const LAS bf16x8*)(lds + PG8_SA(b, h) + aoff + m * 2048 + k * 1024); } while (0)
; #define PG8_LDB(dst, b, h) do { _Pragma("unroll") for (int n = 0; n < 2; ++n) _Pragma("unroll") for (int k = 0; k < 2; ++k) dst[n][k] = *(const LAS bf16x8*)(lds + PG8_SB(b, h) + boff + n * 2048 + k * 1024); } while (0)
; #define PG8_MMA(ai, bj, At, Bt) do { __builtin_amdgcn_s_setprio(1); _Pragma("unroll") for (int m = 0; m < 4; ++m) _Pragma("unroll") for (int n = 0; n < 2; ++n) _Pragma("unroll") for (int k = 0; k < 2; ++k) \
;         acc[ai][bj][m][n] = __builtin_amdgcn_mfma_f32_16x16x32_bf16(Bt[n][k], At[m][k], acc[ai][bj][m][n], 0, 0, 0); __builtin_amdgcn_s_setprio(0); } while (0)
; #define PG8_WAIT_V(n) asm volatile("s_waitcnt vmcnt(" #n ")" ::: "memory")
; #define PG8_WAIT_L(n) asm volatile("s_waitcnt lgkmcnt(" #n ")" ::: "memory")
; #define PG8_BAR __builtin_amdgcn_s_barrier()
; #define PG8_SCHED __builtin_amdgcn_sched_barrier(0)
; template <class Epi, bool DYN = false>
; __device__ __forceinline__ void gemm_phase(LAS unsigned char* lds, const Gemm g, const Epi& E, int wave, unsigned* ctr = nullptr) {
;     ...
;             PG8_BAR; PG8_WAIT_L(0); PG8_MMA(1, 0, At, B0); PG8_BAR; PG8_SCHED;
;             PG8_STAGE(PG8_SB(0, 1), b2 + hstepB, voffB);
;             PG8_WAIT_V(6); PG8_BAR; PG8_MMA(1, 1, At, B1); PG8_BAR;
;             PG8_LDB(B0, 1, 0); PG8_SCHED; PG8_LDA(At, 1, 0); PG8_STAGE(PG8_SA(0, 1), a2 + hstepA, voffA);
;             PG8_WAIT_L(8); PG8_BAR; PG8_WAIT_L(0); PG8_MMA(0, 0, At, B0); PG8_BAR; PG8_SCHED;
;             PG8_LDB(B1, 1, 1); PG8_STAGE(PG8_SB(1, 0), b3, voffB);
	s_add_u32 s0, s70, 0x4000
	s_addc_u32 s1, s71, 0
	s_add_i32 s9, s10, s17
	v_lshl_add_u64 v[130:131], s[0:1], 0, v[178:179]
	s_mov_b32 m0, s9
	s_nop 0
	global_load_lds_dwordx4 v[130:131], off
	v_lshl_add_u64 v[130:131], s[0:1], 0, v[182:183]
	s_add_i32 m0, s9, 0x2000
	s_nop 0
	global_load_lds_dwordx4 v[130:131], off
	s_waitcnt vmcnt(6)
	s_barrier
	s_setprio 1
	v_mfma_f32_16x16x32_bf16 v[98:101], v[196:199], v[146:149], v[98:101]
	v_mfma_f32_16x16x32_bf16 v[90:93], v[208:211], v[146:149], v[90:93]
	v_mfma_f32_16x16x32_bf16 v[82:85], v[196:199], v[154:157], v[82:85]
	v_mfma_f32_16x16x32_bf16 v[74:77], v[208:211], v[154:157], v[74:77]
	v_mfma_f32_16x16x32_bf16 v[66:69], v[196:199], v[162:165], v[66:69]
	v_mfma_f32_16x16x32_bf16 v[58:61], v[208:211], v[162:165], v[58:61]
	v_mfma_f32_16x16x32_bf16 v[50:53], v[196:199], v[170:173], v[50:53]
	v_mfma_f32_16x16x32_bf16 v[30:33], v[208:211], v[170:173], v[30:33]
	v_mfma_f32_16x16x32_bf16 v[98:101], v[204:207], v[150:153], v[98:101]
	v_mfma_f32_16x16x32_bf16 v[90:93], v[212:215], v[150:153], v[90:93]
	v_mfma_f32_16x16x32_bf16 v[82:85], v[204:207], v[158:161], v[82:85]
	v_mfma_f32_16x16x32_bf16 v[74:77], v[212:215], v[158:161], v[74:77]
	v_mfma_f32_16x16x32_bf16 v[66:69], v[204:207], v[166:169], v[66:69]
	v_mfma_f32_16x16x32_bf16 v[58:61], v[212:215], v[166:169], v[58:61]
	v_mfma_f32_16x16x32_bf16 v[50:53], v[204:207], v[174:177], v[50:53]
	v_mfma_f32_16x16x32_bf16 v[30:33], v[212:215], v[174:177], v[30:33]
	s_setprio 0
	s_add_i32 s9, 0, 0x18000
	v_add_u32_e32 v130, s9, v200
	s_barrier
	ds_read_b128 v[196:199], v130
	ds_read_b128 v[204:207], v130 offset:1024
	ds_read_b128 v[208:211], v130 offset:2048
	ds_read_b128 v[212:215], v130 offset:3072
	s_add_u32 s0, s74, 0x80000
	s_addc_u32 s1, s75, 0
	s_mov_b32 m0, s28
	v_lshl_add_u64 v[130:131], s[0:1], 0, v[0:1]
	ds_read_b128 v[146:149], v202 offset:32768
	ds_read_b128 v[150:153], v202 offset:33792
	ds_read_b128 v[154:157], v202 offset:34816
	ds_read_b128 v[158:161], v202 offset:35840
	ds_read_b128 v[162:165], v202 offset:36864
	ds_read_b128 v[166:169], v202 offset:37888
	ds_read_b128 v[170:173], v202 offset:38912
	ds_read_b128 v[174:177], v202 offset:39936
	global_load_lds_dwordx4 v[130:131], off
	v_lshl_add_u64 v[130:131], s[0:1], 0, v[180:181]
	s_mov_b32 m0, s33
	s_nop 0
	global_load_lds_dwordx4 v[130:131], off
	s_waitcnt lgkmcnt(8)
	s_barrier
	s_waitcnt lgkmcnt(0)
	s_setprio 1
	s_waitcnt lgkmcnt(0)
	v_mfma_f32_16x16x32_bf16 v[126:129], v[196:199], v[146:149], v[126:129]
	v_mfma_f32_16x16x32_bf16 v[122:125], v[208:211], v[146:149], v[122:125]
	v_mfma_f32_16x16x32_bf16 v[118:121], v[196:199], v[154:157], v[118:121]
	v_mfma_f32_16x16x32_bf16 v[114:117], v[208:211], v[154:157], v[114:117]
	v_mfma_f32_16x16x32_bf16 v[110:113], v[196:199], v[162:165], v[110:113]
	v_mfma_f32_16x16x32_bf16 v[106:109], v[208:211], v[162:165], v[106:109]
	v_mfma_f32_16x16x32_bf16 v[102:105], v[196:199], v[170:173], v[102:105]
	v_mfma_f32_16x16x32_bf16 v[94:97], v[208:211], v[170:173], v[94:97]
	v_mfma_f32_16x16x32_bf16 v[126:129], v[204:207], v[150:153], v[126:129]
	v_mfma_f32_16x16x32_bf16 v[122:125], v[212:215], v[150:153], v[122:125]
	v_mfma_f32_16x16x32_bf16 v[118:121], v[204:207], v[158:161], v[118:121]
	v_mfma_f32_16x16x32_bf16 v[114:117], v[212:215], v[158:161], v[114:117]
	v_mfma_f32_16x16x32_bf16 v[110:113], v[204:207], v[166:169], v[110:113]
	v_mfma_f32_16x16x32_bf16 v[106:109], v[212:215], v[166:169], v[106:109]
	v_mfma_f32_16x16x32_bf16 v[102:105], v[204:207], v[174:177], v[102:105]
	v_mfma_f32_16x16x32_bf16 v[94:97], v[212:215], v[174:177], v[94:97]
	s_setprio 0
	s_barrier
	s_add_u32 s0, s70, 0x8000
	v_add_u32_e32 v130, 0, v200
	s_addc_u32 s1, s71, 0
	s_add_i32 s9, s9, s17
	v_add_u32_e32 v142, 0x1c000, v130
	v_lshl_add_u64 v[220:221], s[0:1], 0, v[178:179]
	s_mov_b32 m0, s9
	ds_read_b128 v[130:133], v142
	ds_read_b128 v[134:137], v142 offset:1024
	ds_read_b128 v[138:141], v142 offset:2048
	ds_read_b128 v[142:145], v142 offset:3072
	global_load_lds_dwordx4 v[220:221], off
	v_lshl_add_u64 v[220:221], s[0:1], 0, v[182:183]
	s_add_i32 m0, s9, 0x2000
	s_nop 0
	global_load_lds_dwordx4 v[220:221], off
	s_barrier
; #define PG8_STAGE(bufoff, gbase, voff) do { _Pragma("unroll") for (int _i = 0; _i < 2; ++_i) \
;         __builtin_amdgcn_global_load_lds((const unsigned*)((const char*)(gbase) + (voff)[_i]), (LAS unsigned*)(lds + (bufoff) + ldsw + _i * 8192), 16, 0, 0); } while (0)
; #define PG8_LDA(dst, b, h) do { _Pragma("unroll") for (int m = 0; m < 4; ++m) _Pragma("unroll") for (int k = 0; k < 2; ++k) dst[m][k] = *(const LAS bf16x8*)(lds + PG8_SA(b, h) + aoff + m * 2048 + k * 1024); } while (0)
; #define PG8_MMA(ai, bj, At, Bt) do { __builtin_amdgcn_s_setprio(1); _Pragma("unroll") for (int m = 0; m < 4; ++m) _Pragma("unroll") for (int n = 0; n < 2; ++n) _Pragma("unroll") for (int k = 0; k < 2; ++k) \
;         acc[ai][bj][m][n] = __builtin_amdgcn_mfma_f32_16x16x32_bf16(Bt[n][k], At[m][k], acc[ai][bj][m][n], 0, 0, 0); __builtin_amdgcn_s_setprio(0); } while (0)
; #define PG8_WAIT_V(n) asm volatile("s_waitcnt vmcnt(" #n ")" ::: "memory")
; #define PG8_WAIT_L(n) asm volatile("s_waitcnt lgkmcnt(" #n ")" ::: "memory")
; #define PG8_BAR __builtin_amdgcn_s_barrier()
; #define PG8_SCHED __builtin_amdgcn_sched_barrier(0)
; template <class Epi, bool DYN = false>
; __device__ __forceinline__ void gemm_phase(LAS unsigned char* lds, const Gemm g, const Epi& E, int wave, unsigned* ctr = nullptr) {
;     ...
;     auto publish = [&](int si) { if (tid == 0) { int wg = -1;
;             if (ticket < rng_cnt(xcd)) wg = rng_start(xcd) + ticket;
;             else { for (int k = 1; k < 8; ++k) { const int x2 = (xcd + k) & 7; const int t2 = (int)__hip_atomic_fetch_add(ctr + x2 * 16, 1u, __ATOMIC_RELAXED, __HIP_MEMORY_SCOPE_AGENT); if (t2 < rng_cnt(x2)) { wg = rng_start(x2) + t2; break; } } }
;             slot[si] = wg; } };
;     ...
;             PG8_BAR; PG8_WAIT_L(0); PG8_MMA(0, 1, At, B1); PG8_BAR;
;             PG8_LDA(At, 1, 1); PG8_STAGE(PG8_SA(1, 0), a3, voffA);
;             PG8_BAR; PG8_WAIT_L(0); PG8_MMA(1, 0, At, B0); PG8_BAR; PG8_SCHED;
;             if (DYN && t == 0) publish((ui + 1) & 1);
;             PG8_STAGE(PG8_SB(1, 1), b3 + hstepB, voffB);
;             PG8_WAIT_V(6); PG8_BAR; PG8_MMA(1, 1, At, B1); PG8_BAR;
	s_waitcnt lgkmcnt(0)
	s_setprio 1
	s_waitcnt lgkmcnt(0)
	v_mfma_f32_16x16x32_bf16 v[86:89], v[130:133], v[146:149], v[86:89]
	v_mfma_f32_16x16x32_bf16 v[78:81], v[138:141], v[146:149], v[78:81]
	v_mfma_f32_16x16x32_bf16 v[70:73], v[130:133], v[154:157], v[70:73]
	v_mfma_f32_16x16x32_bf16 v[62:65], v[138:141], v[154:157], v[62:65]
	v_mfma_f32_16x16x32_bf16 v[54:57], v[130:133], v[162:165], v[54:57]
	v_mfma_f32_16x16x32_bf16 v[46:49], v[138:141], v[162:165], v[46:49]
	v_mfma_f32_16x16x32_bf16 v[42:45], v[130:133], v[170:173], v[42:45]
	v_mfma_f32_16x16x32_bf16 v[38:41], v[138:141], v[170:173], v[38:41]
	v_mfma_f32_16x16x32_bf16 v[86:89], v[134:137], v[150:153], v[86:89]
	v_mfma_f32_16x16x32_bf16 v[78:81], v[142:145], v[150:153], v[78:81]
	v_mfma_f32_16x16x32_bf16 v[70:73], v[134:137], v[158:161], v[70:73]
	v_mfma_f32_16x16x32_bf16 v[62:65], v[142:145], v[158:161], v[62:65]
	v_mfma_f32_16x16x32_bf16 v[54:57], v[134:137], v[166:169], v[54:57]
	v_mfma_f32_16x16x32_bf16 v[46:49], v[142:145], v[166:169], v[46:49]
	v_mfma_f32_16x16x32_bf16 v[42:45], v[134:137], v[174:177], v[42:45]
	v_mfma_f32_16x16x32_bf16 v[38:41], v[142:145], v[174:177], v[38:41]
	s_setprio 0
	s_mov_b32 m0, s41
	v_lshl_add_u64 v[216:217], v[216:217], 0, s[52:53]
	s_barrier
	ds_read_b128 v[170:173], v202 offset:49152
	ds_read_b128 v[174:177], v202 offset:50176
	ds_read_b128 v[162:165], v202 offset:51200
	ds_read_b128 v[166:169], v202 offset:52224
	ds_read_b128 v[154:157], v202 offset:53248
	ds_read_b128 v[158:161], v202 offset:54272
	ds_read_b128 v[146:149], v202 offset:55296
	ds_read_b128 v[150:153], v202 offset:56320
	global_load_lds_dwordx4 v[216:217], off
	v_lshl_add_u64 v[216:217], v[218:219], 0, s[52:53]
	s_mov_b32 m0, s43
	s_nop 0
	global_load_lds_dwordx4 v[216:217], off
	s_barrier
	s_waitcnt lgkmcnt(0)
	s_setprio 1
	s_waitcnt lgkmcnt(0)
	v_mfma_f32_16x16x32_bf16 v[34:37], v[196:199], v[170:173], v[34:37]
	v_mfma_f32_16x16x32_bf16 v[26:29], v[208:211], v[170:173], v[26:29]
	v_mfma_f32_16x16x32_bf16 v[22:25], v[196:199], v[162:165], v[22:25]
	v_mfma_f32_16x16x32_bf16 v[18:21], v[208:211], v[162:165], v[18:21]
	v_mfma_f32_16x16x32_bf16 v[14:17], v[196:199], v[154:157], v[14:17]
	v_mfma_f32_16x16x32_bf16 v[10:13], v[208:211], v[154:157], v[10:13]
	v_mfma_f32_16x16x32_bf16 v[6:9], v[196:199], v[146:149], v[6:9]
	v_mfma_f32_16x16x32_bf16 v[2:5], v[208:211], v[146:149], v[2:5]
	v_mfma_f32_16x16x32_bf16 v[34:37], v[204:207], v[174:177], v[34:37]
	v_mfma_f32_16x16x32_bf16 v[26:29], v[212:215], v[174:177], v[26:29]
	v_mfma_f32_16x16x32_bf16 v[22:25], v[204:207], v[166:169], v[22:25]
	v_mfma_f32_16x16x32_bf16 v[18:21], v[212:215], v[166:169], v[18:21]
	v_mfma_f32_16x16x32_bf16 v[14:17], v[204:207], v[158:161], v[14:17]
	v_mfma_f32_16x16x32_bf16 v[10:13], v[212:215], v[158:161], v[10:13]
	v_mfma_f32_16x16x32_bf16 v[6:9], v[204:207], v[150:153], v[6:9]
	v_mfma_f32_16x16x32_bf16 v[2:5], v[212:215], v[150:153], v[2:5]
	s_setprio 0
	s_barrier
	s_cmp_lg_u32 s8, 0
	s_cbranch_scc1 .LBB0_81
	v_or_b32_e32 v196, s8, v192
	v_cmp_eq_u32_e64 s[38:39], 0, v196
	s_and_saveexec_b64 s[74:75], s[38:39]
	s_cbranch_execz .LBB0_81
	v_cmp_lt_i32_e32 vcc, s91, v193
	v_add_u32_e32 v203, s23, v193
	v_mov_b32_e32 v204, v203
	s_and_saveexec_b64 s[36:37], vcc
	s_cbranch_execz .LBB0_80
	v_mov_b64_e32 v[196:197], s[44:45]
	s_waitcnt vmcnt(0)
	flat_atomic_add v196, v[196:197], v224 sc0
	s_waitcnt vmcnt(0) lgkmcnt(0)
	v_cmp_lt_i32_e64 s[38:39], s91, v196
	v_add_u32_e32 v204, s2, v196
	s_and_saveexec_b64 s[0:1], s[38:39]
	s_cbranch_execz .LBB0_79
	v_mov_b64_e32 v[196:197], s[58:59]
	flat_atomic_add v196, v[196:197], v224 sc0
	s_waitcnt vmcnt(0) lgkmcnt(0)
	v_cmp_lt_i32_e64 s[38:39], s91, v196
	v_add_u32_e32 v204, s66, v196
	s_and_saveexec_b64 s[80:81], s[38:39]
	s_cbranch_execz .LBB0_78
	v_mov_b64_e32 v[196:197], s[60:61]
	flat_atomic_add v196, v[196:197], v224 sc0
	s_movk_i32 s9, 0x60
	s_waitcnt vmcnt(0) lgkmcnt(0)
	v_cmp_lt_i32_e64 s[38:39], s91, v196
	v_add_u32_e32 v204, s67, v196
	s_and_saveexec_b64 s[82:83], s[38:39]
	s_cbranch_execz .LBB0_77
	v_mov_b64_e32 v[196:197], s[62:63]
	flat_atomic_add v196, v[196:197], v224 sc0
	s_waitcnt vmcnt(0) lgkmcnt(0)
	v_cmp_lt_i32_e64 s[38:39], s91, v196
	v_add_u32_e32 v204, s22, v196
	s_and_saveexec_b64 s[84:85], s[38:39]
	s_cbranch_execz .LBB0_76
	v_mov_b64_e32 v[196:197], s[92:93]
	flat_atomic_add v196, v[196:197], v224 sc0
	v_readlane_b32 s10, v255, 2
	s_waitcnt vmcnt(0) lgkmcnt(0)
	v_cmp_lt_i32_e64 s[38:39], s91, v196
	v_add_u32_e32 v204, s10, v196
	s_and_saveexec_b64 s[86:87], s[38:39]
	s_cbranch_execz .LBB0_75
	v_readlane_b32 s38, v255, 4
	v_readlane_b32 s39, v255, 5
	v_readlane_b32 s10, v255, 6
	s_nop 0
	v_mov_b64_e32 v[196:197], s[38:39]
	flat_atomic_add v196, v[196:197], v224 sc0
	s_waitcnt vmcnt(0) lgkmcnt(0)
	v_cmp_lt_i32_e64 s[38:39], s91, v196
	v_add_u32_e32 v204, s10, v196
	s_and_saveexec_b64 s[88:89], s[38:39]
	s_cbranch_execz .LBB0_74
	v_readlane_b32 s38, v255, 8
	v_readlane_b32 s39, v255, 9
	v_readlane_b32 s10, v255, 10
	s_nop 0
	v_mov_b64_e32 v[196:197], s[38:39]
	flat_atomic_add v196, v[196:197], v224 sc0
	s_waitcnt vmcnt(0) lgkmcnt(0)
	v_add_u32_e32 v197, s10, v196
	v_cmp_gt_i32_e64 s[38:39], s9, v196
	s_nop 1
	v_cndmask_b32_e64 v204, -1, v197, s[38:39]
	s_branch .LBB0_74

; #define PG8_STAGE(bufoff, gbase, voff) do { _Pragma("unroll") for (int _i = 0; _i < 2; ++_i) \
;         __builtin_amdgcn_global_load_lds((const unsigned*)((const char*)(gbase) + (voff)[_i]), (LAS unsigned*)(lds + (bufoff) + ldsw + _i * 8192), 16, 0, 0); } while (0)
; #define PG8_LDA(dst, b, h) do { _Pragma("unroll") for (int m = 0; m < 4; ++m) _Pragma("unroll") for (int k = 0; k < 2; ++k) dst[m][k] = *(const LAS bf16x8*)(lds + PG8_SA(b, h) + aoff + m * 2048 + k * 1024); } while (0)
; #define PG8_LDB(dst, b, h) do { _Pragma("unroll") for (int n = 0; n < 2; ++n) _Pragma("unroll") for (int k = 0; k < 2; ++k) dst[n][k] = *(const LAS bf16x8*)(lds + PG8_SB(b, h) + boff + n * 2048 + k * 1024); } while (0)
; #define PG8_WAIT_V(n) asm volatile("s_waitcnt vmcnt(" #n ")" ::: "memory")
; template <class Epi, bool DYN = false>
; __device__ __forceinline__ void gemm_phase(LAS unsigned char* lds, const Gemm g, const Epi& E, int wave, unsigned* ctr = nullptr) {
;     ...
;             const bool last = (t == nt - 2);
;             if (DYN && last) { const int nw = __builtin_amdgcn_readfirstlane(slot[(ui + 1) & 1]); has_next = nw >= 0;
;                 if (has_next) { decode(nw, nxt); nA = (const char*)g.A + (size_t)nxt.pm * tstepA; nB = (const char*)g.Bt + (size_t)nxt.pn * tstepB; } }
;             const char* a1 = cA + (size_t)(t + 1) * kstepA;
;             const char* a2 = last ? nA : cA + (size_t)(t + 2) * kstepA; const char* b2 = last ? nB : cB + (size_t)(t + 2) * kstepB;
;             const char* a3 = a2 + kstepA; const char* b3 = b2 + kstepB;
;             PG8_LDB(B0, 0, 0); PG8_SCHED; PG8_LDA(At, 0, 0); PG8_STAGE(PG8_SA(1, 1), a1 + hstepA, voffA);
;             PG8_WAIT_L(8); PG8_BAR; PG8_WAIT_L(0); PG8_MMA(0, 0, At, B0); PG8_BAR; PG8_SCHED;
;             PG8_LDB(B1, 0, 1); PG8_STAGE(PG8_SB(0, 0), b2, voffB);
;             PG8_BAR; PG8_WAIT_L(0); PG8_MMA(0, 1, At, B1); PG8_BAR;
;             PG8_LDA(At, 0, 1); PG8_STAGE(PG8_SA(0, 0), a2, voffA);
;             PG8_BAR; PG8_WAIT_L(0); PG8_MMA(1, 0, At, B0); PG8_BAR; PG8_SCHED;
;             PG8_STAGE(PG8_SB(0, 1), b2 + hstepB, voffB);
;             PG8_WAIT_V(6); PG8_BAR; PG8_MMA(1, 1, At, B1); PG8_BAR;
;             PG8_LDB(B0, 1, 0); PG8_SCHED; PG8_LDA(At, 1, 0); PG8_STAGE(PG8_SA(0, 1), a2 + hstepA, voffA);
;             PG8_WAIT_L(8); PG8_BAR; PG8_WAIT_L(0); PG8_MMA(0, 0, At, B0); PG8_BAR; PG8_SCHED;
.LBB0_510:
	s_add_i32 s3, s3, 2
	s_add_u32 s0, s74, s40
	s_addc_u32 s1, s75, s41
	s_add_u32 s4, s0, 0x10000
	s_addc_u32 s5, s1, 0
	s_and_b64 s[0:1], s[36:37], exec
	s_cselect_b32 s43, s77, s5
	s_cselect_b32 s42, s76, s4
	s_add_u32 s4, s19, s40
	s_addc_u32 s5, s15, s41
	s_add_u32 s38, s42, 0x8000
	s_addc_u32 s39, s43, 0
	s_add_i32 s6, 0, 0x10000
	v_add_u32_e32 v142, s6, v201
	ds_read_b128 v[130:133], v142
	ds_read_b128 v[134:137], v142 offset:1024
	ds_read_b128 v[138:141], v142 offset:2048
	ds_read_b128 v[142:145], v142 offset:3072
	s_and_b64 s[0:1], s[36:37], exec
	s_cselect_b32 s37, s67, s5
	s_cselect_b32 s36, s66, s4
	v_lshl_add_u64 v[196:197], v[210:211], 0, s[40:41]
	s_add_i32 m0, s45, 0xc000
	ds_read_b128 v[146:149], v212
	ds_read_b128 v[150:153], v212 offset:1024
	ds_read_b128 v[154:157], v212 offset:2048
	ds_read_b128 v[158:161], v212 offset:3072
	ds_read_b128 v[162:165], v212 offset:4096
	ds_read_b128 v[166:169], v212 offset:5120
	ds_read_b128 v[170:173], v212 offset:6144
	ds_read_b128 v[174:177], v212 offset:7168
	global_load_lds_dwordx4 v[196:197], off
	v_lshl_add_u64 v[196:197], v[208:209], 0, s[40:41]
	s_add_i32 m0, s45, 0xe000
	s_nop 0
	global_load_lds_dwordx4 v[196:197], off
	s_waitcnt lgkmcnt(8)
	s_barrier
	s_waitcnt lgkmcnt(0)
	s_setprio 1
	s_waitcnt lgkmcnt(0)
	v_mfma_f32_16x16x32_bf16 v[2:5], v[130:133], v[146:149], v[2:5]
	v_mfma_f32_16x16x32_bf16 v[30:33], v[138:141], v[146:149], v[30:33]
	v_mfma_f32_16x16x32_bf16 v[26:29], v[130:133], v[154:157], v[26:29]
	v_mfma_f32_16x16x32_bf16 v[22:25], v[138:141], v[154:157], v[22:25]
	v_mfma_f32_16x16x32_bf16 v[18:21], v[130:133], v[162:165], v[18:21]
	v_mfma_f32_16x16x32_bf16 v[14:17], v[138:141], v[162:165], v[14:17]
	v_mfma_f32_16x16x32_bf16 v[10:13], v[130:133], v[170:173], v[10:13]
	v_mfma_f32_16x16x32_bf16 v[6:9], v[138:141], v[170:173], v[6:9]
	v_mfma_f32_16x16x32_bf16 v[2:5], v[134:137], v[150:153], v[2:5]
	v_mfma_f32_16x16x32_bf16 v[30:33], v[142:145], v[150:153], v[30:33]
	v_mfma_f32_16x16x32_bf16 v[26:29], v[134:137], v[158:161], v[26:29]
	v_mfma_f32_16x16x32_bf16 v[22:25], v[142:145], v[158:161], v[22:25]
	v_mfma_f32_16x16x32_bf16 v[18:21], v[134:137], v[166:169], v[18:21]
	v_mfma_f32_16x16x32_bf16 v[14:17], v[142:145], v[166:169], v[14:17]
	v_mfma_f32_16x16x32_bf16 v[10:13], v[134:137], v[174:177], v[10:13]
	v_mfma_f32_16x16x32_bf16 v[6:9], v[142:145], v[174:177], v[6:9]
	s_setprio 0
	s_barrier
	s_add_i32 s4, 0, 0x14000
	s_add_i32 s0, s6, s81
	v_add_u32_e32 v232, s4, v201
	v_lshl_add_u64 v[244:245], s[36:37], 0, v[0:1]
	s_mov_b32 m0, s0
	ds_read_b128 v[196:199], v232
	ds_read_b128 v[214:217], v232 offset:1024
	ds_read_b128 v[218:221], v232 offset:2048
	ds_read_b128 v[232:235], v232 offset:3072
	global_load_lds_dwordx4 v[244:245], off
	v_lshl_add_u64 v[244:245], s[36:37], 0, v[182:183]
	s_add_i32 m0, s0, 0x2000
	s_nop 0
	global_load_lds_dwordx4 v[244:245], off
	s_barrier
	s_waitcnt lgkmcnt(0)
	s_setprio 1
	s_waitcnt lgkmcnt(0)
	v_mfma_f32_16x16x32_bf16 v[94:97], v[196:199], v[146:149], v[94:97]
	v_mfma_f32_16x16x32_bf16 v[90:93], v[218:221], v[146:149], v[90:93]
	v_mfma_f32_16x16x32_bf16 v[86:89], v[196:199], v[154:157], v[86:89]
	v_mfma_f32_16x16x32_bf16 v[82:85], v[218:221], v[154:157], v[82:85]
	v_mfma_f32_16x16x32_bf16 v[78:81], v[196:199], v[162:165], v[78:81]
	v_mfma_f32_16x16x32_bf16 v[74:77], v[218:221], v[162:165], v[74:77]
	v_mfma_f32_16x16x32_bf16 v[70:73], v[196:199], v[170:173], v[70:73]
	v_mfma_f32_16x16x32_bf16 v[66:69], v[218:221], v[170:173], v[66:69]
	v_mfma_f32_16x16x32_bf16 v[94:97], v[214:217], v[150:153], v[94:97]
	v_mfma_f32_16x16x32_bf16 v[90:93], v[232:235], v[150:153], v[90:93]
	v_mfma_f32_16x16x32_bf16 v[86:89], v[214:217], v[158:161], v[86:89]
	v_mfma_f32_16x16x32_bf16 v[82:85], v[232:235], v[158:161], v[82:85]
	v_mfma_f32_16x16x32_bf16 v[78:81], v[214:217], v[166:169], v[78:81]
	v_mfma_f32_16x16x32_bf16 v[74:77], v[232:235], v[166:169], v[74:77]
	v_mfma_f32_16x16x32_bf16 v[70:73], v[214:217], v[174:177], v[70:73]
	v_mfma_f32_16x16x32_bf16 v[66:69], v[232:235], v[174:177], v[66:69]
	s_setprio 0
	s_mov_b32 m0, s45
	v_lshl_add_u64 v[244:245], s[42:43], 0, v[178:179]
	s_barrier
	ds_read_b128 v[146:149], v212 offset:16384
	ds_read_b128 v[150:153], v212 offset:17408
	ds_read_b128 v[154:157], v212 offset:18432
	ds_read_b128 v[158:161], v212 offset:19456
	ds_read_b128 v[162:165], v212 offset:20480
	ds_read_b128 v[166:169], v212 offset:21504
	ds_read_b128 v[170:173], v212 offset:22528
	ds_read_b128 v[174:177], v212 offset:23552
	global_load_lds_dwordx4 v[244:245], off
	v_lshl_add_u64 v[244:245], s[42:43], 0, v[180:181]
	s_mov_b32 m0, s83
	s_nop 0
	global_load_lds_dwordx4 v[244:245], off
	s_barrier
	s_waitcnt lgkmcnt(0)
	s_setprio 1
	s_waitcnt lgkmcnt(0)
	v_mfma_f32_16x16x32_bf16 v[62:65], v[130:133], v[146:149], v[62:65]
	v_mfma_f32_16x16x32_bf16 v[58:61], v[138:141], v[146:149], v[58:61]
	v_mfma_f32_16x16x32_bf16 v[54:57], v[130:133], v[154:157], v[54:57]
	v_mfma_f32_16x16x32_bf16 v[50:53], v[138:141], v[154:157], v[50:53]
	v_mfma_f32_16x16x32_bf16 v[46:49], v[130:133], v[162:165], v[46:49]
	v_mfma_f32_16x16x32_bf16 v[42:45], v[138:141], v[162:165], v[42:45]
	v_mfma_f32_16x16x32_bf16 v[38:41], v[130:133], v[170:173], v[38:41]
	v_mfma_f32_16x16x32_bf16 v[34:37], v[138:141], v[170:173], v[34:37]
	v_mfma_f32_16x16x32_bf16 v[62:65], v[134:137], v[150:153], v[62:65]
	v_mfma_f32_16x16x32_bf16 v[58:61], v[142:145], v[150:153], v[58:61]
	v_mfma_f32_16x16x32_bf16 v[54:57], v[134:137], v[158:161], v[54:57]
	v_mfma_f32_16x16x32_bf16 v[50:53], v[142:145], v[158:161], v[50:53]
	v_mfma_f32_16x16x32_bf16 v[46:49], v[134:137], v[166:169], v[46:49]
	v_mfma_f32_16x16x32_bf16 v[42:45], v[142:145], v[166:169], v[42:45]
	v_mfma_f32_16x16x32_bf16 v[38:41], v[134:137], v[174:177], v[38:41]
	v_mfma_f32_16x16x32_bf16 v[34:37], v[142:145], v[174:177], v[34:37]
	s_setprio 0
	s_barrier
; #define PG8_STAGE(bufoff, gbase, voff) do { _Pragma("unroll") for (int _i = 0; _i < 2; ++_i) \
;         __builtin_amdgcn_global_load_lds((const unsigned*)((const char*)(gbase) + (voff)[_i]), (LAS unsigned*)(lds + (bufoff) + ldsw + _i * 8192), 16, 0, 0); } while (0)
; #define PG8_LDA(dst, b, h) do { _Pragma("unroll") for (int m = 0; m < 4; ++m) _Pragma("unroll") for (int k = 0; k < 2; ++k) dst[m][k] = *(const LAS bf16x8*)(lds + PG8_SA(b, h) + aoff + m * 2048 + k * 1024); } while (0)
; #define PG8_LDB(dst, b, h) do { _Pragma("unroll") for (int n = 0; n < 2; ++n) _Pragma("unroll") for (int k = 0; k < 2; ++k) dst[n][k] = *(const LAS bf16x8*)(lds + PG8_SB(b, h) + boff + n * 2048 + k * 1024); } while (0)
; #define PG8_MMA(ai, bj, At, Bt) do { __builtin_amdgcn_s_setprio(1); _Pragma("unroll") for (int m = 0; m < 4; ++m) _Pragma("unroll") for (int n = 0; n < 2; ++n) _Pragma("unroll") for (int k = 0; k < 2; ++k) \
;         acc[ai][bj][m][n] = __builtin_amdgcn_mfma_f32_16x16x32_bf16(Bt[n][k], At[m][k], acc[ai][bj][m][n], 0, 0, 0); __builtin_amdgcn_s_setprio(0); } while (0)
; #define PG8_WAIT_V(n) asm volatile("s_waitcnt vmcnt(" #n ")" ::: "memory")
; #define PG8_WAIT_L(n) asm volatile("s_waitcnt lgkmcnt(" #n ")" ::: "memory")
; #define PG8_BAR __builtin_amdgcn_s_barrier()
; #define PG8_SCHED __builtin_amdgcn_sched_barrier(0)
; template <class Epi, bool DYN = false>
; __device__ __forceinline__ void gemm_phase(LAS unsigned char* lds, const Gemm g, const Epi& E, int wave, unsigned* ctr = nullptr) {
;     ...
;             PG8_LDA(At, 0, 1); PG8_STAGE(PG8_SA(0, 0), a2, voffA);
;             PG8_BAR; PG8_WAIT_L(0); PG8_MMA(1, 0, At, B0); PG8_BAR; PG8_SCHED;
;             PG8_STAGE(PG8_SB(0, 1), b2 + hstepB, voffB);
;             PG8_WAIT_V(6); PG8_BAR; PG8_MMA(1, 1, At, B1); PG8_BAR;
;             PG8_LDB(B0, 1, 0); PG8_SCHED; PG8_LDA(At, 1, 0); PG8_STAGE(PG8_SA(0, 1), a2 + hstepA, voffA);
;             PG8_WAIT_L(8); PG8_BAR; PG8_WAIT_L(0); PG8_MMA(0, 0, At, B0); PG8_BAR; PG8_SCHED;
;             PG8_LDB(B1, 1, 1); PG8_STAGE(PG8_SB(1, 0), b3, voffB);
;             PG8_BAR; PG8_WAIT_L(0); PG8_MMA(0, 1, At, B1); PG8_BAR;
;             PG8_LDA(At, 1, 1); PG8_STAGE(PG8_SA(1, 0), a3, voffA);
;             PG8_BAR; PG8_WAIT_L(0); PG8_MMA(1, 0, At, B0); PG8_BAR; PG8_SCHED;
	s_add_u32 s0, s36, 0x4000
	s_addc_u32 s1, s37, 0
	s_add_i32 s4, s4, s81
	v_lshl_add_u64 v[130:131], s[0:1], 0, v[0:1]
	s_mov_b32 m0, s4
	s_nop 0
	global_load_lds_dwordx4 v[130:131], off
	v_lshl_add_u64 v[130:131], s[0:1], 0, v[182:183]
	s_add_i32 m0, s4, 0x2000
	s_nop 0
	global_load_lds_dwordx4 v[130:131], off
	s_waitcnt vmcnt(6)
	s_barrier
	s_setprio 1
	v_mfma_f32_16x16x32_bf16 v[126:129], v[196:199], v[146:149], v[126:129]
	v_mfma_f32_16x16x32_bf16 v[122:125], v[218:221], v[146:149], v[122:125]
	v_mfma_f32_16x16x32_bf16 v[118:121], v[196:199], v[154:157], v[118:121]
	v_mfma_f32_16x16x32_bf16 v[114:117], v[218:221], v[154:157], v[114:117]
	v_mfma_f32_16x16x32_bf16 v[110:113], v[196:199], v[162:165], v[110:113]
	v_mfma_f32_16x16x32_bf16 v[106:109], v[218:221], v[162:165], v[106:109]
	v_mfma_f32_16x16x32_bf16 v[102:105], v[196:199], v[170:173], v[102:105]
	v_mfma_f32_16x16x32_bf16 v[98:101], v[218:221], v[170:173], v[98:101]
	v_mfma_f32_16x16x32_bf16 v[126:129], v[214:217], v[150:153], v[126:129]
	v_mfma_f32_16x16x32_bf16 v[122:125], v[232:235], v[150:153], v[122:125]
	v_mfma_f32_16x16x32_bf16 v[118:121], v[214:217], v[158:161], v[118:121]
	v_mfma_f32_16x16x32_bf16 v[114:117], v[232:235], v[158:161], v[114:117]
	v_mfma_f32_16x16x32_bf16 v[110:113], v[214:217], v[166:169], v[110:113]
	v_mfma_f32_16x16x32_bf16 v[106:109], v[232:235], v[166:169], v[106:109]
	v_mfma_f32_16x16x32_bf16 v[102:105], v[214:217], v[174:177], v[102:105]
	v_mfma_f32_16x16x32_bf16 v[98:101], v[232:235], v[174:177], v[98:101]
	s_setprio 0
	s_add_i32 s4, 0, 0x18000
	v_add_u32_e32 v130, s4, v201
	s_barrier
	ds_read_b128 v[196:199], v130
	ds_read_b128 v[214:217], v130 offset:1024
	ds_read_b128 v[218:221], v130 offset:2048
	ds_read_b128 v[232:235], v130 offset:3072
	s_add_u32 s0, s42, 0x4000
	s_addc_u32 s1, s43, 0
	s_mov_b32 m0, s84
	v_lshl_add_u64 v[130:131], s[0:1], 0, v[178:179]
	ds_read_b128 v[146:149], v212 offset:32768
	ds_read_b128 v[150:153], v212 offset:33792
	ds_read_b128 v[154:157], v212 offset:34816
	ds_read_b128 v[158:161], v212 offset:35840
	ds_read_b128 v[162:165], v212 offset:36864
	ds_read_b128 v[166:169], v212 offset:37888
	ds_read_b128 v[170:173], v212 offset:38912
	ds_read_b128 v[174:177], v212 offset:39936
	global_load_lds_dwordx4 v[130:131], off
	v_lshl_add_u64 v[130:131], s[0:1], 0, v[180:181]
	s_mov_b32 m0, s85
	s_nop 0
	global_load_lds_dwordx4 v[130:131], off
	s_waitcnt lgkmcnt(8)
	s_barrier
	s_waitcnt lgkmcnt(0)
	s_setprio 1
	s_waitcnt lgkmcnt(0)
	v_mfma_f32_16x16x32_bf16 v[2:5], v[196:199], v[146:149], v[2:5]
	v_mfma_f32_16x16x32_bf16 v[30:33], v[218:221], v[146:149], v[30:33]
	v_mfma_f32_16x16x32_bf16 v[26:29], v[196:199], v[154:157], v[26:29]
	v_mfma_f32_16x16x32_bf16 v[22:25], v[218:221], v[154:157], v[22:25]
	v_mfma_f32_16x16x32_bf16 v[18:21], v[196:199], v[162:165], v[18:21]
	v_mfma_f32_16x16x32_bf16 v[14:17], v[218:221], v[162:165], v[14:17]
	v_mfma_f32_16x16x32_bf16 v[10:13], v[196:199], v[170:173], v[10:13]
	v_mfma_f32_16x16x32_bf16 v[6:9], v[218:221], v[170:173], v[6:9]
	v_mfma_f32_16x16x32_bf16 v[2:5], v[214:217], v[150:153], v[2:5]
	v_mfma_f32_16x16x32_bf16 v[30:33], v[232:235], v[150:153], v[30:33]
	v_mfma_f32_16x16x32_bf16 v[26:29], v[214:217], v[158:161], v[26:29]
	v_mfma_f32_16x16x32_bf16 v[22:25], v[232:235], v[158:161], v[22:25]
	v_mfma_f32_16x16x32_bf16 v[18:21], v[214:217], v[166:169], v[18:21]
	v_mfma_f32_16x16x32_bf16 v[14:17], v[232:235], v[166:169], v[14:17]
	v_mfma_f32_16x16x32_bf16 v[10:13], v[214:217], v[174:177], v[10:13]
	v_mfma_f32_16x16x32_bf16 v[6:9], v[232:235], v[174:177], v[6:9]
	s_setprio 0
	s_barrier
	s_add_u32 s0, s36, 0x8000
	v_add_u32_e32 v130, 0, v201
	s_addc_u32 s1, s37, 0
	s_add_i32 s4, s4, s81
	v_add_u32_e32 v142, 0x1c000, v130
	v_lshl_add_u64 v[244:245], s[0:1], 0, v[0:1]
	s_mov_b32 m0, s4
	ds_read_b128 v[130:133], v142
	ds_read_b128 v[134:137], v142 offset:1024
	ds_read_b128 v[138:141], v142 offset:2048
	ds_read_b128 v[142:145], v142 offset:3072
	global_load_lds_dwordx4 v[244:245], off
	v_lshl_add_u64 v[244:245], s[0:1], 0, v[182:183]
	s_add_i32 m0, s4, 0x2000
	s_nop 0
	global_load_lds_dwordx4 v[244:245], off
	s_barrier
	s_waitcnt lgkmcnt(0)
	s_setprio 1
	s_waitcnt lgkmcnt(0)
	v_mfma_f32_16x16x32_bf16 v[94:97], v[130:133], v[146:149], v[94:97]
	v_mfma_f32_16x16x32_bf16 v[90:93], v[138:141], v[146:149], v[90:93]
	v_mfma_f32_16x16x32_bf16 v[86:89], v[130:133], v[154:157], v[86:89]
	v_mfma_f32_16x16x32_bf16 v[82:85], v[138:141], v[154:157], v[82:85]
	v_mfma_f32_16x16x32_bf16 v[78:81], v[130:133], v[162:165], v[78:81]
	v_mfma_f32_16x16x32_bf16 v[74:77], v[138:141], v[162:165], v[74:77]
	v_mfma_f32_16x16x32_bf16 v[70:73], v[130:133], v[170:173], v[70:73]
	v_mfma_f32_16x16x32_bf16 v[66:69], v[138:141], v[170:173], v[66:69]
	v_mfma_f32_16x16x32_bf16 v[94:97], v[134:137], v[150:153], v[94:97]
	v_mfma_f32_16x16x32_bf16 v[90:93], v[142:145], v[150:153], v[90:93]
	v_mfma_f32_16x16x32_bf16 v[86:89], v[134:137], v[158:161], v[86:89]
	v_mfma_f32_16x16x32_bf16 v[82:85], v[142:145], v[158:161], v[82:85]
	v_mfma_f32_16x16x32_bf16 v[78:81], v[134:137], v[166:169], v[78:81]
	v_mfma_f32_16x16x32_bf16 v[74:77], v[142:145], v[166:169], v[74:77]
	v_mfma_f32_16x16x32_bf16 v[70:73], v[134:137], v[174:177], v[70:73]
	v_mfma_f32_16x16x32_bf16 v[66:69], v[142:145], v[174:177], v[66:69]
	s_setprio 0
	s_mov_b32 m0, s86
	v_lshl_add_u64 v[244:245], s[38:39], 0, v[178:179]
	s_barrier
; #define PG8_STAGE(bufoff, gbase, voff) do { _Pragma("unroll") for (int _i = 0; _i < 2; ++_i) \
;         __builtin_amdgcn_global_load_lds((const unsigned*)((const char*)(gbase) + (voff)[_i]), (LAS unsigned*)(lds + (bufoff) + ldsw + _i * 8192), 16, 0, 0); } while (0)
; #define PG8_LDA(dst, b, h) do { _Pragma("unroll") for (int m = 0; m < 4; ++m) _Pragma("unroll") for (int k = 0; k < 2; ++k) dst[m][k] = *(const LAS bf16x8*)(lds + PG8_SA(b, h) + aoff + m * 2048 + k * 1024); } while (0)
; #define PG8_LDB(dst, b, h) do { _Pragma("unroll") for (int n = 0; n < 2; ++n) _Pragma("unroll") for (int k = 0; k < 2; ++k) dst[n][k] = *(const LAS bf16x8*)(lds + PG8_SB(b, h) + boff + n * 2048 + k * 1024); } while (0)
; #define PG8_MMA(ai, bj, At, Bt) do { __builtin_amdgcn_s_setprio(1); _Pragma("unroll") for (int m = 0; m < 4; ++m) _Pragma("unroll") for (int n = 0; n < 2; ++n) _Pragma("unroll") for (int k = 0; k < 2; ++k) \
;         acc[ai][bj][m][n] = __builtin_amdgcn_mfma_f32_16x16x32_bf16(Bt[n][k], At[m][k], acc[ai][bj][m][n], 0, 0, 0); __builtin_amdgcn_s_setprio(0); } while (0)
; template <class Epi, bool DYN = false>
; __device__ __forceinline__ void gemm_phase(LAS unsigned char* lds, const Gemm g, const Epi& E, int wave, unsigned* ctr = nullptr) {
;     ...
;     auto publish = [&](int si) { if (tid == 0) { int wg = -1;
;             if (ticket < rng_cnt(xcd)) wg = rng_start(xcd) + ticket;
;             else { for (int k = 1; k < 8; ++k) { const int x2 = (xcd + k) & 7; const int t2 = (int)__hip_atomic_fetch_add(ctr + x2 * 16, 1u, __ATOMIC_RELAXED, __HIP_MEMORY_SCOPE_AGENT); if (t2 < rng_cnt(x2)) { wg = rng_start(x2) + t2; break; } } }
;             slot[si] = wg; } };
;     ...
;             PG8_LDB(B0, 1, 0); PG8_SCHED; PG8_LDA(At, 1, 0); PG8_STAGE(PG8_SA(0, 1), a2 + hstepA, voffA);
;             PG8_WAIT_L(8); PG8_BAR; PG8_WAIT_L(0); PG8_MMA(0, 0, At, B0); PG8_BAR; PG8_SCHED;
;             PG8_LDB(B1, 1, 1); PG8_STAGE(PG8_SB(1, 0), b3, voffB);
;             PG8_BAR; PG8_WAIT_L(0); PG8_MMA(0, 1, At, B1); PG8_BAR;
;             PG8_LDA(At, 1, 1); PG8_STAGE(PG8_SA(1, 0), a3, voffA);
;             PG8_BAR; PG8_WAIT_L(0); PG8_MMA(1, 0, At, B0); PG8_BAR; PG8_SCHED;
;             if (DYN && t == 0) publish((ui + 1) & 1);
;             PG8_STAGE(PG8_SB(1, 1), b3 + hstepB, voffB);
;             PG8_WAIT_V(6); PG8_BAR; PG8_MMA(1, 1, At, B1); PG8_BAR;
	ds_read_b128 v[170:173], v212 offset:49152
	ds_read_b128 v[174:177], v212 offset:50176
	ds_read_b128 v[162:165], v212 offset:51200
	ds_read_b128 v[166:169], v212 offset:52224
	ds_read_b128 v[154:157], v212 offset:53248
	ds_read_b128 v[158:161], v212 offset:54272
	ds_read_b128 v[146:149], v212 offset:55296
	ds_read_b128 v[150:153], v212 offset:56320
	global_load_lds_dwordx4 v[244:245], off
	v_lshl_add_u64 v[244:245], s[38:39], 0, v[180:181]
	s_mov_b32 m0, s87
	s_nop 0
	global_load_lds_dwordx4 v[244:245], off
	s_barrier
	s_waitcnt lgkmcnt(0)
	s_setprio 1
	s_waitcnt lgkmcnt(0)
	v_mfma_f32_16x16x32_bf16 v[62:65], v[196:199], v[170:173], v[62:65]
	v_mfma_f32_16x16x32_bf16 v[58:61], v[218:221], v[170:173], v[58:61]
	v_mfma_f32_16x16x32_bf16 v[54:57], v[196:199], v[162:165], v[54:57]
	v_mfma_f32_16x16x32_bf16 v[50:53], v[218:221], v[162:165], v[50:53]
	v_mfma_f32_16x16x32_bf16 v[46:49], v[196:199], v[154:157], v[46:49]
	v_mfma_f32_16x16x32_bf16 v[42:45], v[218:221], v[154:157], v[42:45]
	v_mfma_f32_16x16x32_bf16 v[38:41], v[196:199], v[146:149], v[38:41]
	v_mfma_f32_16x16x32_bf16 v[34:37], v[218:221], v[146:149], v[34:37]
	v_mfma_f32_16x16x32_bf16 v[62:65], v[214:217], v[174:177], v[62:65]
	v_mfma_f32_16x16x32_bf16 v[58:61], v[232:235], v[174:177], v[58:61]
	v_mfma_f32_16x16x32_bf16 v[54:57], v[214:217], v[166:169], v[54:57]
	v_mfma_f32_16x16x32_bf16 v[50:53], v[232:235], v[166:169], v[50:53]
	v_mfma_f32_16x16x32_bf16 v[46:49], v[214:217], v[158:161], v[46:49]
	v_mfma_f32_16x16x32_bf16 v[42:45], v[232:235], v[158:161], v[42:45]
	v_mfma_f32_16x16x32_bf16 v[38:41], v[214:217], v[150:153], v[38:41]
	v_mfma_f32_16x16x32_bf16 v[34:37], v[232:235], v[150:153], v[34:37]
	s_setprio 0
	s_barrier
	s_cmp_lg_u32 s3, 0
	s_cbranch_scc1 .LBB0_505
	v_or_b32_e32 v196, s3, v187
	v_cmp_eq_u32_e64 s[38:39], 0, v196
	s_and_saveexec_b64 s[42:43], s[38:39]
	s_cbranch_execz .LBB0_505
	v_readlane_b32 s0, v254, 49
	v_cmp_lt_i32_e32 vcc, 0x287, v189
	s_nop 1
	v_add_u32_e32 v213, s0, v189
	v_mov_b32_e32 v214, v213
	s_and_saveexec_b64 s[46:47], vcc
	s_cbranch_execz .LBB0_504
	v_mov_b64_e32 v[196:197], s[50:51]
	s_waitcnt vmcnt(0)
	flat_atomic_add v196, v[196:197], v224 sc0
	s_movk_i32 s0, 0x287
	s_waitcnt vmcnt(0) lgkmcnt(0)
	v_cmp_lt_i32_e64 s[38:39], s0, v196
	v_add_u32_e32 v214, s80, v196
	s_and_saveexec_b64 s[0:1], s[38:39]
	s_cbranch_execz .LBB0_503
	v_mov_b64_e32 v[196:197], s[54:55]
	flat_atomic_add v196, v[196:197], v224 sc0
	s_movk_i32 s4, 0x287
	s_waitcnt vmcnt(0) lgkmcnt(0)
	v_cmp_lt_i32_e64 s[38:39], s4, v196
	v_add_u32_e32 v214, s82, v196
	s_and_saveexec_b64 s[60:61], s[38:39]
	s_cbranch_execz .LBB0_502
	v_mov_b64_e32 v[196:197], s[58:59]
	flat_atomic_add v196, v[196:197], v224 sc0
	s_waitcnt vmcnt(0) lgkmcnt(0)
	v_cmp_lt_i32_e64 s[38:39], s4, v196
	v_add_u32_e32 v214, s17, v196
	s_and_saveexec_b64 s[62:63], s[38:39]
	s_cbranch_execz .LBB0_501
	v_mov_b64_e32 v[196:197], s[90:91]
	flat_atomic_add v196, v[196:197], v224 sc0
	s_waitcnt vmcnt(0) lgkmcnt(0)
	v_cmp_lt_i32_e64 s[38:39], s4, v196
	v_add_u32_e32 v214, s23, v196
	s_and_saveexec_b64 s[64:65], s[38:39]
	s_cbranch_execz .LBB0_500
	v_readlane_b32 s4, v255, 0
	v_readlane_b32 s5, v255, 1
	s_nop 1
	v_mov_b64_e32 v[196:197], s[4:5]
	flat_atomic_add v196, v[196:197], v224 sc0
	s_movk_i32 s4, 0x287
	s_waitcnt vmcnt(0) lgkmcnt(0)
	v_cmp_lt_i32_e64 s[38:39], s4, v196
	v_readlane_b32 s4, v255, 2
	s_nop 1
	v_add_u32_e32 v214, s4, v196
	s_and_saveexec_b64 s[68:69], s[38:39]
	s_cbranch_execz .LBB0_499
	v_readlane_b32 s4, v255, 4
	v_readlane_b32 s5, v255, 5
	s_nop 1
	v_mov_b64_e32 v[196:197], s[4:5]
	flat_atomic_add v196, v[196:197], v224 sc0
	s_movk_i32 s4, 0x287
	s_waitcnt vmcnt(0) lgkmcnt(0)
	v_cmp_lt_i32_e64 s[38:39], s4, v196
	v_readlane_b32 s4, v255, 6
	s_nop 1
	v_add_u32_e32 v214, s4, v196
	s_and_saveexec_b64 s[70:71], s[38:39]
	s_cbranch_execz .LBB0_498
	v_readlane_b32 s4, v255, 8
	v_readlane_b32 s5, v255, 9
	s_nop 1
	v_mov_b64_e32 v[196:197], s[4:5]
	flat_atomic_add v196, v[196:197], v224 sc0
	v_readlane_b32 s4, v255, 10
	s_waitcnt vmcnt(0) lgkmcnt(0)
	s_nop 0
	v_add_u32_e32 v197, s4, v196
	s_movk_i32 s4, 0x288
	v_cmp_gt_i32_e64 s[38:39], s4, v196
	s_nop 1
	v_cndmask_b32_e64 v214, -1, v197, s[38:39]
	s_branch .LBB0_498

; #define PG8_STAGE(bufoff, gbase, voff) do { _Pragma("unroll") for (int _i = 0; _i < 2; ++_i) \
;         __builtin_amdgcn_global_load_lds((const unsigned*)((const char*)(gbase) + (voff)[_i]), (LAS unsigned*)(lds + (bufoff) + ldsw + _i * 8192), 16, 0, 0); } while (0)
; #define PG8_LDA(dst, b, h) do { _Pragma("unroll") for (int m = 0; m < 4; ++m) _Pragma("unroll") for (int k = 0; k < 2; ++k) dst[m][k] = *(const LAS bf16x8*)(lds + PG8_SA(b, h) + aoff + m * 2048 + k * 1024); } while (0)
; #define PG8_LDB(dst, b, h) do { _Pragma("unroll") for (int n = 0; n < 2; ++n) _Pragma("unroll") for (int k = 0; k < 2; ++k) dst[n][k] = *(const LAS bf16x8*)(lds + PG8_SB(b, h) + boff + n * 2048 + k * 1024); } while (0)
; #define PG8_WAIT_V(n) asm volatile("s_waitcnt vmcnt(" #n ")" ::: "memory")
; template <class Epi, bool DYN = false>
; __device__ __forceinline__ void gemm_phase(LAS unsigned char* lds, const Gemm g, const Epi& E, int wave, unsigned* ctr = nullptr) {
;     ...
;             const bool last = (t == nt - 2);
;             if (DYN && last) { const int nw = __builtin_amdgcn_readfirstlane(slot[(ui + 1) & 1]); has_next = nw >= 0;
;                 if (has_next) { decode(nw, nxt); nA = (const char*)g.A + (size_t)nxt.pm * tstepA; nB = (const char*)g.Bt + (size_t)nxt.pn * tstepB; } }
;             const char* a1 = cA + (size_t)(t + 1) * kstepA;
;             const char* a2 = last ? nA : cA + (size_t)(t + 2) * kstepA; const char* b2 = last ? nB : cB + (size_t)(t + 2) * kstepB;
;             const char* a3 = a2 + kstepA; const char* b3 = b2 + kstepB;
;             PG8_LDB(B0, 0, 0); PG8_SCHED; PG8_LDA(At, 0, 0); PG8_STAGE(PG8_SA(1, 1), a1 + hstepA, voffA);
;             PG8_WAIT_L(8); PG8_BAR; PG8_WAIT_L(0); PG8_MMA(0, 0, At, B0); PG8_BAR; PG8_SCHED;
;             PG8_LDB(B1, 0, 1); PG8_STAGE(PG8_SB(0, 0), b2, voffB);
;             PG8_BAR; PG8_WAIT_L(0); PG8_MMA(0, 1, At, B1); PG8_BAR;
;             PG8_LDA(At, 0, 1); PG8_STAGE(PG8_SA(0, 0), a2, voffA);
;             PG8_BAR; PG8_WAIT_L(0); PG8_MMA(1, 0, At, B0); PG8_BAR; PG8_SCHED;
;             PG8_STAGE(PG8_SB(0, 1), b2 + hstepB, voffB);
;             PG8_WAIT_V(6); PG8_BAR; PG8_MMA(1, 1, At, B1); PG8_BAR;
;             PG8_LDB(B0, 1, 0); PG8_SCHED; PG8_LDA(At, 1, 0); PG8_STAGE(PG8_SA(0, 1), a2 + hstepA, voffA);
;             PG8_WAIT_L(8); PG8_BAR; PG8_WAIT_L(0); PG8_MMA(0, 0, At, B0); PG8_BAR; PG8_SCHED;
.LBB0_852:
	s_add_i32 s10, s10, 2
	s_add_u32 s0, s62, s68
	s_addc_u32 s1, s63, s69
	s_add_u32 s38, s0, 0x10000
	s_addc_u32 s39, s1, 0
	s_and_b64 s[0:1], s[70:71], exec
	s_cselect_b32 s73, s47, s39
	s_cselect_b32 s72, s46, s38
	s_add_u32 s74, s7, s68
	s_addc_u32 s75, s8, s69
	s_add_u32 s38, s72, 0x8000
	s_addc_u32 s39, s73, 0
	s_add_i32 s76, 0, 0x10000
	v_add_u32_e32 v142, s76, v200
	ds_read_b128 v[130:133], v142
	ds_read_b128 v[134:137], v142 offset:1024
	ds_read_b128 v[138:141], v142 offset:2048
	ds_read_b128 v[142:145], v142 offset:3072
	s_and_b64 s[0:1], s[70:71], exec
	s_cselect_b32 s71, s27, s75
	s_cselect_b32 s70, s26, s74
	v_lshl_add_u64 v[196:197], v[190:191], 0, s[68:69]
	s_add_i32 m0, s33, 0xc000
	ds_read_b128 v[146:149], v202
	ds_read_b128 v[150:153], v202 offset:1024
	ds_read_b128 v[154:157], v202 offset:2048
	ds_read_b128 v[158:161], v202 offset:3072
	ds_read_b128 v[162:165], v202 offset:4096
	ds_read_b128 v[166:169], v202 offset:5120
	ds_read_b128 v[170:173], v202 offset:6144
	ds_read_b128 v[174:177], v202 offset:7168
	global_load_lds_dwordx4 v[196:197], off
	v_lshl_add_u64 v[196:197], v[188:189], 0, s[68:69]
	s_add_i32 m0, s33, 0xe000
	s_nop 0
	global_load_lds_dwordx4 v[196:197], off
	s_waitcnt lgkmcnt(8)
	s_barrier
	s_waitcnt lgkmcnt(0)
	s_setprio 1
	s_waitcnt lgkmcnt(0)
	v_mfma_f32_16x16x32_bf16 v[126:129], v[130:133], v[146:149], v[126:129]
	v_mfma_f32_16x16x32_bf16 v[122:125], v[138:141], v[146:149], v[122:125]
	v_mfma_f32_16x16x32_bf16 v[118:121], v[130:133], v[154:157], v[118:121]
	v_mfma_f32_16x16x32_bf16 v[114:117], v[138:141], v[154:157], v[114:117]
	v_mfma_f32_16x16x32_bf16 v[110:113], v[130:133], v[162:165], v[110:113]
	v_mfma_f32_16x16x32_bf16 v[106:109], v[138:141], v[162:165], v[106:109]
	v_mfma_f32_16x16x32_bf16 v[102:105], v[130:133], v[170:173], v[102:105]
	v_mfma_f32_16x16x32_bf16 v[94:97], v[138:141], v[170:173], v[94:97]
	v_mfma_f32_16x16x32_bf16 v[126:129], v[134:137], v[150:153], v[126:129]
	v_mfma_f32_16x16x32_bf16 v[122:125], v[142:145], v[150:153], v[122:125]
	v_mfma_f32_16x16x32_bf16 v[118:121], v[134:137], v[158:161], v[118:121]
	v_mfma_f32_16x16x32_bf16 v[114:117], v[142:145], v[158:161], v[114:117]
	v_mfma_f32_16x16x32_bf16 v[110:113], v[134:137], v[166:169], v[110:113]
	v_mfma_f32_16x16x32_bf16 v[106:109], v[142:145], v[166:169], v[106:109]
	v_mfma_f32_16x16x32_bf16 v[102:105], v[134:137], v[174:177], v[102:105]
	v_mfma_f32_16x16x32_bf16 v[94:97], v[142:145], v[174:177], v[94:97]
	s_setprio 0
	s_barrier
	s_add_i32 s74, 0, 0x14000
	s_add_i32 s0, s76, s28
	v_add_u32_e32 v212, s74, v200
	v_lshl_add_u64 v[216:217], s[70:71], 0, v[0:1]
	s_mov_b32 m0, s0
	ds_read_b128 v[196:199], v212
	ds_read_b128 v[204:207], v212 offset:1024
	ds_read_b128 v[208:211], v212 offset:2048
	ds_read_b128 v[212:215], v212 offset:3072
	global_load_lds_dwordx4 v[216:217], off
	v_lshl_add_u64 v[216:217], s[70:71], 0, v[182:183]
	s_add_i32 m0, s0, 0x2000
	s_nop 0
	global_load_lds_dwordx4 v[216:217], off
	s_barrier
	s_waitcnt lgkmcnt(0)
	s_setprio 1
	s_waitcnt lgkmcnt(0)
	v_mfma_f32_16x16x32_bf16 v[90:93], v[196:199], v[146:149], v[90:93]
	v_mfma_f32_16x16x32_bf16 v[82:85], v[208:211], v[146:149], v[82:85]
	v_mfma_f32_16x16x32_bf16 v[74:77], v[196:199], v[154:157], v[74:77]
	v_mfma_f32_16x16x32_bf16 v[66:69], v[208:211], v[154:157], v[66:69]
	v_mfma_f32_16x16x32_bf16 v[58:61], v[196:199], v[162:165], v[58:61]
	v_mfma_f32_16x16x32_bf16 v[50:53], v[208:211], v[162:165], v[50:53]
	v_mfma_f32_16x16x32_bf16 v[42:45], v[196:199], v[170:173], v[42:45]
	v_mfma_f32_16x16x32_bf16 v[38:41], v[208:211], v[170:173], v[38:41]
	v_mfma_f32_16x16x32_bf16 v[90:93], v[204:207], v[150:153], v[90:93]
	v_mfma_f32_16x16x32_bf16 v[82:85], v[212:215], v[150:153], v[82:85]
	v_mfma_f32_16x16x32_bf16 v[74:77], v[204:207], v[158:161], v[74:77]
	v_mfma_f32_16x16x32_bf16 v[66:69], v[212:215], v[158:161], v[66:69]
	v_mfma_f32_16x16x32_bf16 v[58:61], v[204:207], v[166:169], v[58:61]
	v_mfma_f32_16x16x32_bf16 v[50:53], v[212:215], v[166:169], v[50:53]
	v_mfma_f32_16x16x32_bf16 v[42:45], v[204:207], v[174:177], v[42:45]
	v_mfma_f32_16x16x32_bf16 v[38:41], v[212:215], v[174:177], v[38:41]
	s_setprio 0
	s_mov_b32 m0, s33
	v_lshl_add_u64 v[216:217], s[72:73], 0, v[178:179]
	s_barrier
	ds_read_b128 v[146:149], v202 offset:16384
	ds_read_b128 v[150:153], v202 offset:17408
	ds_read_b128 v[154:157], v202 offset:18432
	ds_read_b128 v[158:161], v202 offset:19456
	ds_read_b128 v[162:165], v202 offset:20480
	ds_read_b128 v[166:169], v202 offset:21504
	ds_read_b128 v[170:173], v202 offset:22528
	ds_read_b128 v[174:177], v202 offset:23552
	global_load_lds_dwordx4 v[216:217], off
	v_lshl_add_u64 v[216:217], s[72:73], 0, v[180:181]
	s_mov_b32 m0, s48
	s_nop 0
	global_load_lds_dwordx4 v[216:217], off
	s_barrier
	s_waitcnt lgkmcnt(0)
	s_setprio 1
	s_waitcnt lgkmcnt(0)
	v_mfma_f32_16x16x32_bf16 v[34:37], v[130:133], v[146:149], v[34:37]
	v_mfma_f32_16x16x32_bf16 v[26:29], v[138:141], v[146:149], v[26:29]
	v_mfma_f32_16x16x32_bf16 v[22:25], v[130:133], v[154:157], v[22:25]
	v_mfma_f32_16x16x32_bf16 v[18:21], v[138:141], v[154:157], v[18:21]
	v_mfma_f32_16x16x32_bf16 v[14:17], v[130:133], v[162:165], v[14:17]
	v_mfma_f32_16x16x32_bf16 v[10:13], v[138:141], v[162:165], v[10:13]
	v_mfma_f32_16x16x32_bf16 v[6:9], v[130:133], v[170:173], v[6:9]
	v_mfma_f32_16x16x32_bf16 v[2:5], v[138:141], v[170:173], v[2:5]
	v_mfma_f32_16x16x32_bf16 v[34:37], v[134:137], v[150:153], v[34:37]
	v_mfma_f32_16x16x32_bf16 v[26:29], v[142:145], v[150:153], v[26:29]
	v_mfma_f32_16x16x32_bf16 v[22:25], v[134:137], v[158:161], v[22:25]
	v_mfma_f32_16x16x32_bf16 v[18:21], v[142:145], v[158:161], v[18:21]
	v_mfma_f32_16x16x32_bf16 v[14:17], v[134:137], v[166:169], v[14:17]
	v_mfma_f32_16x16x32_bf16 v[10:13], v[142:145], v[166:169], v[10:13]
	v_mfma_f32_16x16x32_bf16 v[6:9], v[134:137], v[174:177], v[6:9]
	v_mfma_f32_16x16x32_bf16 v[2:5], v[142:145], v[174:177], v[2:5]
	s_setprio 0
	s_barrier
; #define PG8_STAGE(bufoff, gbase, voff) do { _Pragma("unroll") for (int _i = 0; _i < 2; ++_i) \
;         __builtin_amdgcn_global_load_lds((const unsigned*)((const char*)(gbase) + (voff)[_i]), (LAS unsigned*)(lds + (bufoff) + ldsw + _i * 8192), 16, 0, 0); } while (0)
; #define PG8_LDA(dst, b, h) do { _Pragma("unroll") for (int m = 0; m < 4; ++m) _Pragma("unroll") for (int k = 0; k < 2; ++k) dst[m][k] = *(const LAS bf16x8*)(lds + PG8_SA(b, h) + aoff + m * 2048 + k * 1024); } while (0)
; #define PG8_LDB(dst, b, h) do { _Pragma("unroll") for (int n = 0; n < 2; ++n) _Pragma("unroll") for (int k = 0; k < 2; ++k) dst[n][k] = *(const LAS bf16x8*)(lds + PG8_SB(b, h) + boff + n * 2048 + k * 1024); } while (0)
; #define PG8_MMA(ai, bj, At, Bt) do { __builtin_amdgcn_s_setprio(1); _Pragma("unroll") for (int m = 0; m < 4; ++m) _Pragma("unroll") for (int n = 0; n < 2; ++n) _Pragma("unroll") for (int k = 0; k < 2; ++k) \
;         acc[ai][bj][m][n] = __builtin_amdgcn_mfma_f32_16x16x32_bf16(Bt[n][k], At[m][k], acc[ai][bj][m][n], 0, 0, 0); __builtin_amdgcn_s_setprio(0); } while (0)
; #define PG8_WAIT_V(n) asm volatile("s_waitcnt vmcnt(" #n ")" ::: "memory")
; #define PG8_WAIT_L(n) asm volatile("s_waitcnt lgkmcnt(" #n ")" ::: "memory")
; #define PG8_BAR __builtin_amdgcn_s_barrier()
; #define PG8_SCHED __builtin_amdgcn_sched_barrier(0)
; template <class Epi, bool DYN = false>
; __device__ __forceinline__ void gemm_phase(LAS unsigned char* lds, const Gemm g, const Epi& E, int wave, unsigned* ctr = nullptr) {
;     ...
;             PG8_LDA(At, 0, 1); PG8_STAGE(PG8_SA(0, 0), a2, voffA);
;             PG8_BAR; PG8_WAIT_L(0); PG8_MMA(1, 0, At, B0); PG8_BAR; PG8_SCHED;
;             PG8_STAGE(PG8_SB(0, 1), b2 + hstepB, voffB);
;             PG8_WAIT_V(6); PG8_BAR; PG8_MMA(1, 1, At, B1); PG8_BAR;
;             PG8_LDB(B0, 1, 0); PG8_SCHED; PG8_LDA(At, 1, 0); PG8_STAGE(PG8_SA(0, 1), a2 + hstepA, voffA);
;             PG8_WAIT_L(8); PG8_BAR; PG8_WAIT_L(0); PG8_MMA(0, 0, At, B0); PG8_BAR; PG8_SCHED;
;             PG8_LDB(B1, 1, 1); PG8_STAGE(PG8_SB(1, 0), b3, voffB);
;             PG8_BAR; PG8_WAIT_L(0); PG8_MMA(0, 1, At, B1); PG8_BAR;
;             PG8_LDA(At, 1, 1); PG8_STAGE(PG8_SA(1, 0), a3, voffA);
;             PG8_BAR; PG8_WAIT_L(0); PG8_MMA(1, 0, At, B0); PG8_BAR; PG8_SCHED;
	s_add_u32 s0, s70, 0x4000
	s_addc_u32 s1, s71, 0
	s_add_i32 s74, s74, s28
	v_lshl_add_u64 v[130:131], s[0:1], 0, v[0:1]
	s_mov_b32 m0, s74
	s_nop 0
	global_load_lds_dwordx4 v[130:131], off
	v_lshl_add_u64 v[130:131], s[0:1], 0, v[182:183]
	s_add_i32 m0, s74, 0x2000
	s_nop 0
	global_load_lds_dwordx4 v[130:131], off
	s_waitcnt vmcnt(6)
	s_barrier
	s_setprio 1
	v_mfma_f32_16x16x32_bf16 v[98:101], v[196:199], v[146:149], v[98:101]
	v_mfma_f32_16x16x32_bf16 v[86:89], v[208:211], v[146:149], v[86:89]
	v_mfma_f32_16x16x32_bf16 v[78:81], v[196:199], v[154:157], v[78:81]
	v_mfma_f32_16x16x32_bf16 v[70:73], v[208:211], v[154:157], v[70:73]
	v_mfma_f32_16x16x32_bf16 v[62:65], v[196:199], v[162:165], v[62:65]
	v_mfma_f32_16x16x32_bf16 v[54:57], v[208:211], v[162:165], v[54:57]
	v_mfma_f32_16x16x32_bf16 v[46:49], v[196:199], v[170:173], v[46:49]
	v_mfma_f32_16x16x32_bf16 v[30:33], v[208:211], v[170:173], v[30:33]
	v_mfma_f32_16x16x32_bf16 v[98:101], v[204:207], v[150:153], v[98:101]
	v_mfma_f32_16x16x32_bf16 v[86:89], v[212:215], v[150:153], v[86:89]
	v_mfma_f32_16x16x32_bf16 v[78:81], v[204:207], v[158:161], v[78:81]
	v_mfma_f32_16x16x32_bf16 v[70:73], v[212:215], v[158:161], v[70:73]
	v_mfma_f32_16x16x32_bf16 v[62:65], v[204:207], v[166:169], v[62:65]
	v_mfma_f32_16x16x32_bf16 v[54:57], v[212:215], v[166:169], v[54:57]
	v_mfma_f32_16x16x32_bf16 v[46:49], v[204:207], v[174:177], v[46:49]
	v_mfma_f32_16x16x32_bf16 v[30:33], v[212:215], v[174:177], v[30:33]
	s_setprio 0
	s_add_i32 s74, 0, 0x18000
	v_add_u32_e32 v130, s74, v200
	s_barrier
	ds_read_b128 v[196:199], v130
	ds_read_b128 v[204:207], v130 offset:1024
	ds_read_b128 v[208:211], v130 offset:2048
	ds_read_b128 v[212:215], v130 offset:3072
	s_add_u32 s0, s72, 0x4000
	s_addc_u32 s1, s73, 0
	s_mov_b32 m0, s86
	v_lshl_add_u64 v[130:131], s[0:1], 0, v[178:179]
	ds_read_b128 v[146:149], v202 offset:32768
	ds_read_b128 v[150:153], v202 offset:33792
	ds_read_b128 v[154:157], v202 offset:34816
	ds_read_b128 v[158:161], v202 offset:35840
	ds_read_b128 v[162:165], v202 offset:36864
	ds_read_b128 v[166:169], v202 offset:37888
	ds_read_b128 v[170:173], v202 offset:38912
	ds_read_b128 v[174:177], v202 offset:39936
	global_load_lds_dwordx4 v[130:131], off
	v_lshl_add_u64 v[130:131], s[0:1], 0, v[180:181]
	s_mov_b32 m0, s87
	s_nop 0
	global_load_lds_dwordx4 v[130:131], off
	s_waitcnt lgkmcnt(8)
	s_barrier
	s_waitcnt lgkmcnt(0)
	s_setprio 1
	s_waitcnt lgkmcnt(0)
	v_mfma_f32_16x16x32_bf16 v[126:129], v[196:199], v[146:149], v[126:129]
	v_mfma_f32_16x16x32_bf16 v[122:125], v[208:211], v[146:149], v[122:125]
	v_mfma_f32_16x16x32_bf16 v[118:121], v[196:199], v[154:157], v[118:121]
	v_mfma_f32_16x16x32_bf16 v[114:117], v[208:211], v[154:157], v[114:117]
	v_mfma_f32_16x16x32_bf16 v[110:113], v[196:199], v[162:165], v[110:113]
	v_mfma_f32_16x16x32_bf16 v[106:109], v[208:211], v[162:165], v[106:109]
	v_mfma_f32_16x16x32_bf16 v[102:105], v[196:199], v[170:173], v[102:105]
	v_mfma_f32_16x16x32_bf16 v[94:97], v[208:211], v[170:173], v[94:97]
	v_mfma_f32_16x16x32_bf16 v[126:129], v[204:207], v[150:153], v[126:129]
	v_mfma_f32_16x16x32_bf16 v[122:125], v[212:215], v[150:153], v[122:125]
	v_mfma_f32_16x16x32_bf16 v[118:121], v[204:207], v[158:161], v[118:121]
	v_mfma_f32_16x16x32_bf16 v[114:117], v[212:215], v[158:161], v[114:117]
	v_mfma_f32_16x16x32_bf16 v[110:113], v[204:207], v[166:169], v[110:113]
	v_mfma_f32_16x16x32_bf16 v[106:109], v[212:215], v[166:169], v[106:109]
	v_mfma_f32_16x16x32_bf16 v[102:105], v[204:207], v[174:177], v[102:105]
	v_mfma_f32_16x16x32_bf16 v[94:97], v[212:215], v[174:177], v[94:97]
	s_setprio 0
	s_barrier
	s_add_u32 s0, s70, 0x8000
	v_add_u32_e32 v130, 0, v200
	s_addc_u32 s1, s71, 0
	s_add_i32 s72, s74, s28
	v_add_u32_e32 v142, 0x1c000, v130
	v_lshl_add_u64 v[216:217], s[0:1], 0, v[0:1]
	s_mov_b32 m0, s72
	ds_read_b128 v[130:133], v142
	ds_read_b128 v[134:137], v142 offset:1024
	ds_read_b128 v[138:141], v142 offset:2048
	ds_read_b128 v[142:145], v142 offset:3072
	global_load_lds_dwordx4 v[216:217], off
	v_lshl_add_u64 v[216:217], s[0:1], 0, v[182:183]
	s_add_i32 m0, s72, 0x2000
	s_nop 0
	global_load_lds_dwordx4 v[216:217], off
	s_barrier
; #define PG8_STAGE(bufoff, gbase, voff) do { _Pragma("unroll") for (int _i = 0; _i < 2; ++_i) \
;         __builtin_amdgcn_global_load_lds((const unsigned*)((const char*)(gbase) + (voff)[_i]), (LAS unsigned*)(lds + (bufoff) + ldsw + _i * 8192), 16, 0, 0); } while (0)
; #define PG8_LDA(dst, b, h) do { _Pragma("unroll") for (int m = 0; m < 4; ++m) _Pragma("unroll") for (int k = 0; k < 2; ++k) dst[m][k] = *(const LAS bf16x8*)(lds + PG8_SA(b, h) + aoff + m * 2048 + k * 1024); } while (0)
; #define PG8_MMA(ai, bj, At, Bt) do { __builtin_amdgcn_s_setprio(1); _Pragma("unroll") for (int m = 0; m < 4; ++m) _Pragma("unroll") for (int n = 0; n < 2; ++n) _Pragma("unroll") for (int k = 0; k < 2; ++k) \
;         acc[ai][bj][m][n] = __builtin_amdgcn_mfma_f32_16x16x32_bf16(Bt[n][k], At[m][k], acc[ai][bj][m][n], 0, 0, 0); __builtin_amdgcn_s_setprio(0); } while (0)
; #define PG8_WAIT_V(n) asm volatile("s_waitcnt vmcnt(" #n ")" ::: "memory")
; #define PG8_WAIT_L(n) asm volatile("s_waitcnt lgkmcnt(" #n ")" ::: "memory")
; #define PG8_BAR __builtin_amdgcn_s_barrier()
; #define PG8_SCHED __builtin_amdgcn_sched_barrier(0)
; template <class Epi, bool DYN = false>
; __device__ __forceinline__ void gemm_phase(LAS unsigned char* lds, const Gemm g, const Epi& E, int wave, unsigned* ctr = nullptr) {
;     ...
;     auto publish = [&](int si) { if (tid == 0) { int wg = -1;
;             if (ticket < rng_cnt(xcd)) wg = rng_start(xcd) + ticket;
;             else { for (int k = 1; k < 8; ++k) { const int x2 = (xcd + k) & 7; const int t2 = (int)__hip_atomic_fetch_add(ctr + x2 * 16, 1u, __ATOMIC_RELAXED, __HIP_MEMORY_SCOPE_AGENT); if (t2 < rng_cnt(x2)) { wg = rng_start(x2) + t2; break; } } }
;             slot[si] = wg; } };
;     ...
;             PG8_BAR; PG8_WAIT_L(0); PG8_MMA(0, 1, At, B1); PG8_BAR;
;             PG8_LDA(At, 1, 1); PG8_STAGE(PG8_SA(1, 0), a3, voffA);
;             PG8_BAR; PG8_WAIT_L(0); PG8_MMA(1, 0, At, B0); PG8_BAR; PG8_SCHED;
;             if (DYN && t == 0) publish((ui + 1) & 1);
;             PG8_STAGE(PG8_SB(1, 1), b3 + hstepB, voffB);
;             PG8_WAIT_V(6); PG8_BAR; PG8_MMA(1, 1, At, B1); PG8_BAR;
	s_waitcnt lgkmcnt(0)
	s_setprio 1
	s_waitcnt lgkmcnt(0)
	v_mfma_f32_16x16x32_bf16 v[90:93], v[130:133], v[146:149], v[90:93]
	v_mfma_f32_16x16x32_bf16 v[82:85], v[138:141], v[146:149], v[82:85]
	v_mfma_f32_16x16x32_bf16 v[74:77], v[130:133], v[154:157], v[74:77]
	v_mfma_f32_16x16x32_bf16 v[66:69], v[138:141], v[154:157], v[66:69]
	v_mfma_f32_16x16x32_bf16 v[58:61], v[130:133], v[162:165], v[58:61]
	v_mfma_f32_16x16x32_bf16 v[50:53], v[138:141], v[162:165], v[50:53]
	v_mfma_f32_16x16x32_bf16 v[42:45], v[130:133], v[170:173], v[42:45]
	v_mfma_f32_16x16x32_bf16 v[38:41], v[138:141], v[170:173], v[38:41]
	v_mfma_f32_16x16x32_bf16 v[90:93], v[134:137], v[150:153], v[90:93]
	v_mfma_f32_16x16x32_bf16 v[82:85], v[142:145], v[150:153], v[82:85]
	v_mfma_f32_16x16x32_bf16 v[74:77], v[134:137], v[158:161], v[74:77]
	v_mfma_f32_16x16x32_bf16 v[66:69], v[142:145], v[158:161], v[66:69]
	v_mfma_f32_16x16x32_bf16 v[58:61], v[134:137], v[166:169], v[58:61]
	v_mfma_f32_16x16x32_bf16 v[50:53], v[142:145], v[166:169], v[50:53]
	v_mfma_f32_16x16x32_bf16 v[42:45], v[134:137], v[174:177], v[42:45]
	v_mfma_f32_16x16x32_bf16 v[38:41], v[142:145], v[174:177], v[38:41]
	s_setprio 0
	s_mov_b32 m0, s88
	v_lshl_add_u64 v[216:217], s[38:39], 0, v[178:179]
	s_barrier
	ds_read_b128 v[170:173], v202 offset:49152
	ds_read_b128 v[174:177], v202 offset:50176
	ds_read_b128 v[162:165], v202 offset:51200
	ds_read_b128 v[166:169], v202 offset:52224
	ds_read_b128 v[154:157], v202 offset:53248
	ds_read_b128 v[158:161], v202 offset:54272
	ds_read_b128 v[146:149], v202 offset:55296
	ds_read_b128 v[150:153], v202 offset:56320
	global_load_lds_dwordx4 v[216:217], off
	v_lshl_add_u64 v[216:217], s[38:39], 0, v[180:181]
	s_mov_b32 m0, s89
	s_nop 0
	global_load_lds_dwordx4 v[216:217], off
	s_barrier
	s_waitcnt lgkmcnt(0)
	s_setprio 1
	s_waitcnt lgkmcnt(0)
	v_mfma_f32_16x16x32_bf16 v[34:37], v[196:199], v[170:173], v[34:37]
	v_mfma_f32_16x16x32_bf16 v[26:29], v[208:211], v[170:173], v[26:29]
	v_mfma_f32_16x16x32_bf16 v[22:25], v[196:199], v[162:165], v[22:25]
	v_mfma_f32_16x16x32_bf16 v[18:21], v[208:211], v[162:165], v[18:21]
	v_mfma_f32_16x16x32_bf16 v[14:17], v[196:199], v[154:157], v[14:17]
	v_mfma_f32_16x16x32_bf16 v[10:13], v[208:211], v[154:157], v[10:13]
	v_mfma_f32_16x16x32_bf16 v[6:9], v[196:199], v[146:149], v[6:9]
	v_mfma_f32_16x16x32_bf16 v[2:5], v[208:211], v[146:149], v[2:5]
	v_mfma_f32_16x16x32_bf16 v[34:37], v[204:207], v[174:177], v[34:37]
	v_mfma_f32_16x16x32_bf16 v[26:29], v[212:215], v[174:177], v[26:29]
	v_mfma_f32_16x16x32_bf16 v[22:25], v[204:207], v[166:169], v[22:25]
	v_mfma_f32_16x16x32_bf16 v[18:21], v[212:215], v[166:169], v[18:21]
	v_mfma_f32_16x16x32_bf16 v[14:17], v[204:207], v[158:161], v[14:17]
	v_mfma_f32_16x16x32_bf16 v[10:13], v[212:215], v[158:161], v[10:13]
	v_mfma_f32_16x16x32_bf16 v[6:9], v[204:207], v[150:153], v[6:9]
	v_mfma_f32_16x16x32_bf16 v[2:5], v[212:215], v[150:153], v[2:5]
	s_setprio 0
	s_barrier
	s_cmp_lg_u32 s10, 0
	s_cbranch_scc1 .LBB0_847
	v_or_b32_e32 v196, s10, v192
	v_cmp_eq_u32_e64 s[38:39], 0, v196
	s_and_saveexec_b64 s[72:73], s[38:39]
	s_cbranch_execz .LBB0_847
	v_cmp_lt_i32_e32 vcc, s91, v193
	v_add_u32_e32 v203, s61, v193
	v_mov_b32_e32 v204, v203
	s_and_saveexec_b64 s[74:75], vcc
	s_cbranch_execz .LBB0_846
	v_mov_b64_e32 v[196:197], s[40:41]
	s_waitcnt vmcnt(0)
	flat_atomic_add v196, v[196:197], v224 sc0
	s_waitcnt vmcnt(0) lgkmcnt(0)
	v_cmp_lt_i32_e64 s[38:39], s91, v196
	v_add_u32_e32 v204, s3, v196
	s_and_saveexec_b64 s[0:1], s[38:39]
	s_cbranch_execz .LBB0_845
	v_mov_b64_e32 v[196:197], s[42:43]
	flat_atomic_add v196, v[196:197], v224 sc0
	s_waitcnt vmcnt(0) lgkmcnt(0)
	v_cmp_lt_i32_e64 s[38:39], s91, v196
	v_add_u32_e32 v204, s2, v196
	s_and_saveexec_b64 s[76:77], s[38:39]
	s_cbranch_execz .LBB0_844
	v_mov_b64_e32 v[196:197], s[44:45]
	flat_atomic_add v196, v[196:197], v224 sc0
	s_waitcnt vmcnt(0) lgkmcnt(0)
	v_cmp_lt_i32_e64 s[38:39], s91, v196
	v_add_u32_e32 v204, s22, v196
	s_and_saveexec_b64 s[78:79], s[38:39]
	s_cbranch_execz .LBB0_843
	v_mov_b64_e32 v[196:197], s[50:51]
	flat_atomic_add v196, v[196:197], v224 sc0
	s_waitcnt vmcnt(0) lgkmcnt(0)
	v_cmp_lt_i32_e64 s[38:39], s91, v196
	v_add_u32_e32 v204, s23, v196
	s_and_saveexec_b64 s[80:81], s[38:39]
	s_cbranch_execz .LBB0_842
	v_mov_b64_e32 v[196:197], s[54:55]
	flat_atomic_add v196, v[196:197], v224 sc0
	s_movk_i32 s92, 0x60
	s_waitcnt vmcnt(0) lgkmcnt(0)
	v_cmp_lt_i32_e64 s[38:39], s91, v196
	v_add_u32_e32 v204, s60, v196
	s_and_saveexec_b64 s[82:83], s[38:39]
	s_cbranch_execz .LBB0_841
	v_mov_b64_e32 v[196:197], s[58:59]
	flat_atomic_add v196, v[196:197], v224 sc0
	v_readlane_b32 s84, v254, 52
	s_waitcnt vmcnt(0) lgkmcnt(0)
	v_cmp_lt_i32_e64 s[38:39], s91, v196
	v_add_u32_e32 v204, s84, v196
	s_and_saveexec_b64 s[84:85], s[38:39]
	s_cbranch_execz .LBB0_840
	v_readlane_b32 s38, v254, 54
	v_readlane_b32 s39, v254, 55
	s_nop 1
	v_mov_b64_e32 v[196:197], s[38:39]
	flat_atomic_add v196, v[196:197], v224 sc0
	v_readlane_b32 s38, v254, 56
	s_waitcnt vmcnt(0) lgkmcnt(0)
	s_nop 0
	v_add_u32_e32 v197, s38, v196
	v_cmp_gt_i32_e64 s[38:39], s92, v196
	s_nop 1
	v_cndmask_b32_e64 v204, -1, v197, s[38:39]
	s_branch .LBB0_840

; #define PG8_STAGE(bufoff, gbase, voff) do { _Pragma("unroll") for (int _i = 0; _i < 2; ++_i) \
;         __builtin_amdgcn_global_load_lds((const unsigned*)((const char*)(gbase) + (voff)[_i]), (LAS unsigned*)(lds + (bufoff) + ldsw + _i * 8192), 16, 0, 0); } while (0)
; #define PG8_LDA(dst, b, h) do { _Pragma("unroll") for (int m = 0; m < 4; ++m) _Pragma("unroll") for (int k = 0; k < 2; ++k) dst[m][k] = *(const LAS bf16x8*)(lds + PG8_SA(b, h) + aoff + m * 2048 + k * 1024); } while (0)
; #define PG8_LDB(dst, b, h) do { _Pragma("unroll") for (int n = 0; n < 2; ++n) _Pragma("unroll") for (int k = 0; k < 2; ++k) dst[n][k] = *(const LAS bf16x8*)(lds + PG8_SB(b, h) + boff + n * 2048 + k * 1024); } while (0)
; #define PG8_WAIT_V(n) asm volatile("s_waitcnt vmcnt(" #n ")" ::: "memory")
; template <class Epi, bool DYN = false>
; __device__ __forceinline__ void gemm_phase(LAS unsigned char* lds, const Gemm g, const Epi& E, int wave, unsigned* ctr = nullptr) {
;     ...
;             const bool last = (t == nt - 2);
;             if (DYN && last) { const int nw = __builtin_amdgcn_readfirstlane(slot[(ui + 1) & 1]); has_next = nw >= 0;
;                 if (has_next) { decode(nw, nxt); nA = (const char*)g.A + (size_t)nxt.pm * tstepA; nB = (const char*)g.Bt + (size_t)nxt.pn * tstepB; } }
;             const char* a1 = cA + (size_t)(t + 1) * kstepA;
;             const char* a2 = last ? nA : cA + (size_t)(t + 2) * kstepA; const char* b2 = last ? nB : cB + (size_t)(t + 2) * kstepB;
;             const char* a3 = a2 + kstepA; const char* b3 = b2 + kstepB;
;             PG8_LDB(B0, 0, 0); PG8_SCHED; PG8_LDA(At, 0, 0); PG8_STAGE(PG8_SA(1, 1), a1 + hstepA, voffA);
;             PG8_WAIT_L(8); PG8_BAR; PG8_WAIT_L(0); PG8_MMA(0, 0, At, B0); PG8_BAR; PG8_SCHED;
;             PG8_LDB(B1, 0, 1); PG8_STAGE(PG8_SB(0, 0), b2, voffB);
;             PG8_BAR; PG8_WAIT_L(0); PG8_MMA(0, 1, At, B1); PG8_BAR;
;             PG8_LDA(At, 0, 1); PG8_STAGE(PG8_SA(0, 0), a2, voffA);
;             PG8_BAR; PG8_WAIT_L(0); PG8_MMA(1, 0, At, B0); PG8_BAR; PG8_SCHED;
;             PG8_STAGE(PG8_SB(0, 1), b2 + hstepB, voffB);
;             PG8_WAIT_V(6); PG8_BAR; PG8_MMA(1, 1, At, B1); PG8_BAR;
;             PG8_LDB(B0, 1, 0); PG8_SCHED; PG8_LDA(At, 1, 0); PG8_STAGE(PG8_SA(0, 1), a2 + hstepA, voffA);
;             PG8_WAIT_L(8); PG8_BAR; PG8_WAIT_L(0); PG8_MMA(0, 0, At, B0); PG8_BAR; PG8_SCHED;
.LBB0_924:
	s_add_i32 s7, s7, 2
	s_add_u32 s0, s68, s46
	s_addc_u32 s1, s69, s47
	s_add_u32 s8, s0, 0x10000
	s_addc_u32 s9, s1, 0
	s_and_b64 s[0:1], s[74:75], exec
	s_cselect_b32 s77, s71, s9
	s_cselect_b32 s76, s70, s8
	s_add_u32 s8, s4, s46
	s_addc_u32 s9, s5, s47
	s_add_u32 s38, s76, 0x8000
	s_addc_u32 s39, s77, 0
	s_add_i32 s10, 0, 0x10000
	v_add_u32_e32 v0, s10, v214
	ds_read_b128 v[130:133], v0
	ds_read_b128 v[134:137], v0 offset:1024
	ds_read_b128 v[138:141], v0 offset:2048
	ds_read_b128 v[142:145], v0 offset:3072
	s_and_b64 s[0:1], s[74:75], exec
	s_cselect_b32 s75, s65, s9
	s_cselect_b32 s74, s64, s8
	v_lshl_add_u64 v[196:197], v[200:201], 0, s[46:47]
	s_add_i32 m0, s19, 0xc000
	ds_read_b128 v[146:149], v215
	ds_read_b128 v[150:153], v215 offset:1024
	ds_read_b128 v[154:157], v215 offset:2048
	ds_read_b128 v[158:161], v215 offset:3072
	ds_read_b128 v[162:165], v215 offset:4096
	ds_read_b128 v[166:169], v215 offset:5120
	ds_read_b128 v[170:173], v215 offset:6144
	ds_read_b128 v[174:177], v215 offset:7168
	global_load_lds_dwordx4 v[196:197], off
	v_lshl_add_u64 v[196:197], v[192:193], 0, s[46:47]
	s_add_i32 m0, s19, 0xe000
	s_nop 0
	global_load_lds_dwordx4 v[196:197], off
	s_waitcnt lgkmcnt(8)
	s_barrier
	s_waitcnt lgkmcnt(0)
	s_setprio 1
	s_waitcnt lgkmcnt(0)
	v_mfma_f32_16x16x32_bf16 v[2:5], v[130:133], v[146:149], v[2:5]
	v_mfma_f32_16x16x32_bf16 v[30:33], v[138:141], v[146:149], v[30:33]
	v_mfma_f32_16x16x32_bf16 v[26:29], v[130:133], v[154:157], v[26:29]
	v_mfma_f32_16x16x32_bf16 v[22:25], v[138:141], v[154:157], v[22:25]
	v_mfma_f32_16x16x32_bf16 v[18:21], v[130:133], v[162:165], v[18:21]
	v_mfma_f32_16x16x32_bf16 v[14:17], v[138:141], v[162:165], v[14:17]
	v_mfma_f32_16x16x32_bf16 v[10:13], v[130:133], v[170:173], v[10:13]
	v_mfma_f32_16x16x32_bf16 v[6:9], v[138:141], v[170:173], v[6:9]
	v_mfma_f32_16x16x32_bf16 v[2:5], v[134:137], v[150:153], v[2:5]
	v_mfma_f32_16x16x32_bf16 v[30:33], v[142:145], v[150:153], v[30:33]
	v_mfma_f32_16x16x32_bf16 v[26:29], v[134:137], v[158:161], v[26:29]
	v_mfma_f32_16x16x32_bf16 v[22:25], v[142:145], v[158:161], v[22:25]
	v_mfma_f32_16x16x32_bf16 v[18:21], v[134:137], v[166:169], v[18:21]
	v_mfma_f32_16x16x32_bf16 v[14:17], v[142:145], v[166:169], v[14:17]
	v_mfma_f32_16x16x32_bf16 v[10:13], v[134:137], v[174:177], v[10:13]
	v_mfma_f32_16x16x32_bf16 v[6:9], v[142:145], v[174:177], v[6:9]
	s_setprio 0
	s_barrier
	s_add_i32 s8, 0, 0x14000
	s_add_i32 s0, s10, s17
	v_add_u32_e32 v0, s8, v214
	v_lshl_add_u64 v[220:221], s[74:75], 0, v[180:181]
	s_mov_b32 m0, s0
	ds_read_b128 v[216:219], v0
	ds_read_b128 v[244:247], v0 offset:1024
	ds_read_b128 v[232:235], v0 offset:2048
	ds_read_b128 v[196:199], v0 offset:3072
	global_load_lds_dwordx4 v[220:221], off
	v_lshl_add_u64 v[220:221], s[74:75], 0, v[184:185]
	s_add_i32 m0, s0, 0x2000
	s_nop 0
	global_load_lds_dwordx4 v[220:221], off
	s_barrier
	s_waitcnt lgkmcnt(0)
	s_setprio 1
	s_waitcnt lgkmcnt(0)
	v_mfma_f32_16x16x32_bf16 v[94:97], v[216:219], v[146:149], v[94:97]
	v_mfma_f32_16x16x32_bf16 v[90:93], v[232:235], v[146:149], v[90:93]
	v_mfma_f32_16x16x32_bf16 v[86:89], v[216:219], v[154:157], v[86:89]
	v_mfma_f32_16x16x32_bf16 v[82:85], v[232:235], v[154:157], v[82:85]
	v_mfma_f32_16x16x32_bf16 v[78:81], v[216:219], v[162:165], v[78:81]
	v_mfma_f32_16x16x32_bf16 v[74:77], v[232:235], v[162:165], v[74:77]
	v_mfma_f32_16x16x32_bf16 v[70:73], v[216:219], v[170:173], v[70:73]
	v_mfma_f32_16x16x32_bf16 v[66:69], v[232:235], v[170:173], v[66:69]
	v_mfma_f32_16x16x32_bf16 v[94:97], v[244:247], v[150:153], v[94:97]
	v_mfma_f32_16x16x32_bf16 v[90:93], v[196:199], v[150:153], v[90:93]
	v_mfma_f32_16x16x32_bf16 v[86:89], v[244:247], v[158:161], v[86:89]
	v_mfma_f32_16x16x32_bf16 v[82:85], v[196:199], v[158:161], v[82:85]
	v_mfma_f32_16x16x32_bf16 v[78:81], v[244:247], v[166:169], v[78:81]
	v_mfma_f32_16x16x32_bf16 v[74:77], v[196:199], v[166:169], v[74:77]
	v_mfma_f32_16x16x32_bf16 v[70:73], v[244:247], v[174:177], v[70:73]
	v_mfma_f32_16x16x32_bf16 v[66:69], v[196:199], v[174:177], v[66:69]
	s_setprio 0
	s_mov_b32 m0, s19
	v_lshl_add_u64 v[220:221], s[76:77], 0, v[178:179]
	s_barrier
	ds_read_b128 v[146:149], v215 offset:16384
	ds_read_b128 v[150:153], v215 offset:17408
	ds_read_b128 v[154:157], v215 offset:18432
	ds_read_b128 v[158:161], v215 offset:19456
	ds_read_b128 v[162:165], v215 offset:20480
	ds_read_b128 v[166:169], v215 offset:21504
	ds_read_b128 v[170:173], v215 offset:22528
	ds_read_b128 v[174:177], v215 offset:23552
	global_load_lds_dwordx4 v[220:221], off
	v_lshl_add_u64 v[220:221], s[76:77], 0, v[182:183]
	s_mov_b32 m0, s23
	s_nop 0
	global_load_lds_dwordx4 v[220:221], off
	s_barrier
	s_waitcnt lgkmcnt(0)
	s_setprio 1
	s_waitcnt lgkmcnt(0)
	v_mfma_f32_16x16x32_bf16 v[62:65], v[130:133], v[146:149], v[62:65]
	v_mfma_f32_16x16x32_bf16 v[58:61], v[138:141], v[146:149], v[58:61]
	v_mfma_f32_16x16x32_bf16 v[54:57], v[130:133], v[154:157], v[54:57]
	v_mfma_f32_16x16x32_bf16 v[50:53], v[138:141], v[154:157], v[50:53]
	v_mfma_f32_16x16x32_bf16 v[46:49], v[130:133], v[162:165], v[46:49]
	v_mfma_f32_16x16x32_bf16 v[42:45], v[138:141], v[162:165], v[42:45]
	v_mfma_f32_16x16x32_bf16 v[38:41], v[130:133], v[170:173], v[38:41]
	v_mfma_f32_16x16x32_bf16 v[34:37], v[138:141], v[170:173], v[34:37]
	v_mfma_f32_16x16x32_bf16 v[62:65], v[134:137], v[150:153], v[62:65]
	v_mfma_f32_16x16x32_bf16 v[58:61], v[142:145], v[150:153], v[58:61]
	v_mfma_f32_16x16x32_bf16 v[54:57], v[134:137], v[158:161], v[54:57]
	v_mfma_f32_16x16x32_bf16 v[50:53], v[142:145], v[158:161], v[50:53]
	v_mfma_f32_16x16x32_bf16 v[46:49], v[134:137], v[166:169], v[46:49]
	v_mfma_f32_16x16x32_bf16 v[42:45], v[142:145], v[166:169], v[42:45]
	v_mfma_f32_16x16x32_bf16 v[38:41], v[134:137], v[174:177], v[38:41]
	v_mfma_f32_16x16x32_bf16 v[34:37], v[142:145], v[174:177], v[34:37]
	s_setprio 0
	s_barrier
; #define PG8_STAGE(bufoff, gbase, voff) do { _Pragma("unroll") for (int _i = 0; _i < 2; ++_i) \
;         __builtin_amdgcn_global_load_lds((const unsigned*)((const char*)(gbase) + (voff)[_i]), (LAS unsigned*)(lds + (bufoff) + ldsw + _i * 8192), 16, 0, 0); } while (0)
; #define PG8_LDA(dst, b, h) do { _Pragma("unroll") for (int m = 0; m < 4; ++m) _Pragma("unroll") for (int k = 0; k < 2; ++k) dst[m][k] = *(const LAS bf16x8*)(lds + PG8_SA(b, h) + aoff + m * 2048 + k * 1024); } while (0)
; #define PG8_LDB(dst, b, h) do { _Pragma("unroll") for (int n = 0; n < 2; ++n) _Pragma("unroll") for (int k = 0; k < 2; ++k) dst[n][k] = *(const LAS bf16x8*)(lds + PG8_SB(b, h) + boff + n * 2048 + k * 1024); } while (0)
; #define PG8_MMA(ai, bj, At, Bt) do { __builtin_amdgcn_s_setprio(1); _Pragma("unroll") for (int m = 0; m < 4; ++m) _Pragma("unroll") for (int n = 0; n < 2; ++n) _Pragma("unroll") for (int k = 0; k < 2; ++k) \
;         acc[ai][bj][m][n] = __builtin_amdgcn_mfma_f32_16x16x32_bf16(Bt[n][k], At[m][k], acc[ai][bj][m][n], 0, 0, 0); __builtin_amdgcn_s_setprio(0); } while (0)
; #define PG8_WAIT_V(n) asm volatile("s_waitcnt vmcnt(" #n ")" ::: "memory")
; #define PG8_WAIT_L(n) asm volatile("s_waitcnt lgkmcnt(" #n ")" ::: "memory")
; #define PG8_BAR __builtin_amdgcn_s_barrier()
; #define PG8_SCHED __builtin_amdgcn_sched_barrier(0)
; template <class Epi, bool DYN = false>
; __device__ __forceinline__ void gemm_phase(LAS unsigned char* lds, const Gemm g, const Epi& E, int wave, unsigned* ctr = nullptr) {
;     ...
;             PG8_LDA(At, 0, 1); PG8_STAGE(PG8_SA(0, 0), a2, voffA);
;             PG8_BAR; PG8_WAIT_L(0); PG8_MMA(1, 0, At, B0); PG8_BAR; PG8_SCHED;
;             PG8_STAGE(PG8_SB(0, 1), b2 + hstepB, voffB);
;             PG8_WAIT_V(6); PG8_BAR; PG8_MMA(1, 1, At, B1); PG8_BAR;
;             PG8_LDB(B0, 1, 0); PG8_SCHED; PG8_LDA(At, 1, 0); PG8_STAGE(PG8_SA(0, 1), a2 + hstepA, voffA);
;             PG8_WAIT_L(8); PG8_BAR; PG8_WAIT_L(0); PG8_MMA(0, 0, At, B0); PG8_BAR; PG8_SCHED;
;             PG8_LDB(B1, 1, 1); PG8_STAGE(PG8_SB(1, 0), b3, voffB);
;             PG8_BAR; PG8_WAIT_L(0); PG8_MMA(0, 1, At, B1); PG8_BAR;
;             PG8_LDA(At, 1, 1); PG8_STAGE(PG8_SA(1, 0), a3, voffA);
;             PG8_BAR; PG8_WAIT_L(0); PG8_MMA(1, 0, At, B0); PG8_BAR; PG8_SCHED;
	s_add_u32 s0, s74, 0x4000
	s_addc_u32 s1, s75, 0
	s_add_i32 s8, s8, s17
	v_lshl_add_u64 v[130:131], s[0:1], 0, v[180:181]
	s_mov_b32 m0, s8
	s_nop 0
	global_load_lds_dwordx4 v[130:131], off
	v_lshl_add_u64 v[130:131], s[0:1], 0, v[184:185]
	s_add_i32 m0, s8, 0x2000
	s_nop 0
	global_load_lds_dwordx4 v[130:131], off
	s_waitcnt vmcnt(6)
	s_barrier
	s_setprio 1
	v_mfma_f32_16x16x32_bf16 v[126:129], v[216:219], v[146:149], v[126:129]
	v_mfma_f32_16x16x32_bf16 v[122:125], v[232:235], v[146:149], v[122:125]
	v_mfma_f32_16x16x32_bf16 v[118:121], v[216:219], v[154:157], v[118:121]
	v_mfma_f32_16x16x32_bf16 v[114:117], v[232:235], v[154:157], v[114:117]
	v_mfma_f32_16x16x32_bf16 v[110:113], v[216:219], v[162:165], v[110:113]
	v_mfma_f32_16x16x32_bf16 v[106:109], v[232:235], v[162:165], v[106:109]
	v_mfma_f32_16x16x32_bf16 v[102:105], v[216:219], v[170:173], v[102:105]
	v_mfma_f32_16x16x32_bf16 v[98:101], v[232:235], v[170:173], v[98:101]
	v_mfma_f32_16x16x32_bf16 v[126:129], v[244:247], v[150:153], v[126:129]
	v_mfma_f32_16x16x32_bf16 v[122:125], v[196:199], v[150:153], v[122:125]
	v_mfma_f32_16x16x32_bf16 v[118:121], v[244:247], v[158:161], v[118:121]
	v_mfma_f32_16x16x32_bf16 v[114:117], v[196:199], v[158:161], v[114:117]
	v_mfma_f32_16x16x32_bf16 v[110:113], v[244:247], v[166:169], v[110:113]
	v_mfma_f32_16x16x32_bf16 v[106:109], v[196:199], v[166:169], v[106:109]
	v_mfma_f32_16x16x32_bf16 v[102:105], v[244:247], v[174:177], v[102:105]
	v_mfma_f32_16x16x32_bf16 v[98:101], v[196:199], v[174:177], v[98:101]
	s_setprio 0
	s_add_i32 s8, 0, 0x18000
	v_add_u32_e32 v0, s8, v214
	s_barrier
	ds_read_b128 v[196:199], v0
	ds_read_b128 v[216:219], v0 offset:1024
	ds_read_b128 v[232:235], v0 offset:2048
	ds_read_b128 v[244:247], v0 offset:3072
	s_add_u32 s0, s76, 0x4000
	s_addc_u32 s1, s77, 0
	s_mov_b32 m0, s27
	v_lshl_add_u64 v[130:131], s[0:1], 0, v[178:179]
	ds_read_b128 v[146:149], v215 offset:32768
	ds_read_b128 v[150:153], v215 offset:33792
	ds_read_b128 v[154:157], v215 offset:34816
	ds_read_b128 v[158:161], v215 offset:35840
	ds_read_b128 v[162:165], v215 offset:36864
	ds_read_b128 v[166:169], v215 offset:37888
	ds_read_b128 v[170:173], v215 offset:38912
	ds_read_b128 v[174:177], v215 offset:39936
	global_load_lds_dwordx4 v[130:131], off
	v_lshl_add_u64 v[130:131], s[0:1], 0, v[182:183]
	s_mov_b32 m0, s15
	s_nop 0
	global_load_lds_dwordx4 v[130:131], off
	s_waitcnt lgkmcnt(8)
	s_barrier
	s_waitcnt lgkmcnt(0)
	s_setprio 1
	s_waitcnt lgkmcnt(0)
	v_mfma_f32_16x16x32_bf16 v[2:5], v[196:199], v[146:149], v[2:5]
	v_mfma_f32_16x16x32_bf16 v[30:33], v[232:235], v[146:149], v[30:33]
	v_mfma_f32_16x16x32_bf16 v[26:29], v[196:199], v[154:157], v[26:29]
	v_mfma_f32_16x16x32_bf16 v[22:25], v[232:235], v[154:157], v[22:25]
	v_mfma_f32_16x16x32_bf16 v[18:21], v[196:199], v[162:165], v[18:21]
	v_mfma_f32_16x16x32_bf16 v[14:17], v[232:235], v[162:165], v[14:17]
	v_mfma_f32_16x16x32_bf16 v[10:13], v[196:199], v[170:173], v[10:13]
	v_mfma_f32_16x16x32_bf16 v[6:9], v[232:235], v[170:173], v[6:9]
	v_mfma_f32_16x16x32_bf16 v[2:5], v[216:219], v[150:153], v[2:5]
	v_mfma_f32_16x16x32_bf16 v[30:33], v[244:247], v[150:153], v[30:33]
	v_mfma_f32_16x16x32_bf16 v[26:29], v[216:219], v[158:161], v[26:29]
	v_mfma_f32_16x16x32_bf16 v[22:25], v[244:247], v[158:161], v[22:25]
	v_mfma_f32_16x16x32_bf16 v[18:21], v[216:219], v[166:169], v[18:21]
	v_mfma_f32_16x16x32_bf16 v[14:17], v[244:247], v[166:169], v[14:17]
	v_mfma_f32_16x16x32_bf16 v[10:13], v[216:219], v[174:177], v[10:13]
	v_mfma_f32_16x16x32_bf16 v[6:9], v[244:247], v[174:177], v[6:9]
	s_setprio 0
	s_barrier
	s_add_u32 s0, s74, 0x8000
	v_add_u32_e32 v0, 0, v214
	s_addc_u32 s1, s75, 0
	s_add_i32 s8, s8, s17
	v_add_u32_e32 v0, 0x1c000, v0
	v_lshl_add_u64 v[220:221], s[0:1], 0, v[180:181]
	s_mov_b32 m0, s8
	ds_read_b128 v[130:133], v0
	ds_read_b128 v[134:137], v0 offset:1024
	ds_read_b128 v[138:141], v0 offset:2048
	ds_read_b128 v[142:145], v0 offset:3072
	global_load_lds_dwordx4 v[220:221], off
	v_lshl_add_u64 v[220:221], s[0:1], 0, v[184:185]
	s_add_i32 m0, s8, 0x2000
	s_nop 0
	global_load_lds_dwordx4 v[220:221], off
	s_barrier
; #define PG8_STAGE(bufoff, gbase, voff) do { _Pragma("unroll") for (int _i = 0; _i < 2; ++_i) \
;         __builtin_amdgcn_global_load_lds((const unsigned*)((const char*)(gbase) + (voff)[_i]), (LAS unsigned*)(lds + (bufoff) + ldsw + _i * 8192), 16, 0, 0); } while (0)
; #define PG8_LDA(dst, b, h) do { _Pragma("unroll") for (int m = 0; m < 4; ++m) _Pragma("unroll") for (int k = 0; k < 2; ++k) dst[m][k] = *(const LAS bf16x8*)(lds + PG8_SA(b, h) + aoff + m * 2048 + k * 1024); } while (0)
; #define PG8_MMA(ai, bj, At, Bt) do { __builtin_amdgcn_s_setprio(1); _Pragma("unroll") for (int m = 0; m < 4; ++m) _Pragma("unroll") for (int n = 0; n < 2; ++n) _Pragma("unroll") for (int k = 0; k < 2; ++k) \
;         acc[ai][bj][m][n] = __builtin_amdgcn_mfma_f32_16x16x32_bf16(Bt[n][k], At[m][k], acc[ai][bj][m][n], 0, 0, 0); __builtin_amdgcn_s_setprio(0); } while (0)
; #define PG8_WAIT_V(n) asm volatile("s_waitcnt vmcnt(" #n ")" ::: "memory")
; #define PG8_WAIT_L(n) asm volatile("s_waitcnt lgkmcnt(" #n ")" ::: "memory")
; #define PG8_BAR __builtin_amdgcn_s_barrier()
; #define PG8_SCHED __builtin_amdgcn_sched_barrier(0)
; template <class Epi, bool DYN = false>
; __device__ __forceinline__ void gemm_phase(LAS unsigned char* lds, const Gemm g, const Epi& E, int wave, unsigned* ctr = nullptr) {
;     ...
;     auto publish = [&](int si) { if (tid == 0) { int wg = -1;
;             if (ticket < rng_cnt(xcd)) wg = rng_start(xcd) + ticket;
;             else { for (int k = 1; k < 8; ++k) { const int x2 = (xcd + k) & 7; const int t2 = (int)__hip_atomic_fetch_add(ctr + x2 * 16, 1u, __ATOMIC_RELAXED, __HIP_MEMORY_SCOPE_AGENT); if (t2 < rng_cnt(x2)) { wg = rng_start(x2) + t2; break; } } }
;             slot[si] = wg; } };
;     ...
;             PG8_BAR; PG8_WAIT_L(0); PG8_MMA(0, 1, At, B1); PG8_BAR;
;             PG8_LDA(At, 1, 1); PG8_STAGE(PG8_SA(1, 0), a3, voffA);
;             PG8_BAR; PG8_WAIT_L(0); PG8_MMA(1, 0, At, B0); PG8_BAR; PG8_SCHED;
;             if (DYN && t == 0) publish((ui + 1) & 1);
;             PG8_STAGE(PG8_SB(1, 1), b3 + hstepB, voffB);
;             PG8_WAIT_V(6); PG8_BAR; PG8_MMA(1, 1, At, B1); PG8_BAR;
	s_waitcnt lgkmcnt(0)
	s_setprio 1
	s_waitcnt lgkmcnt(0)
	v_mfma_f32_16x16x32_bf16 v[94:97], v[130:133], v[146:149], v[94:97]
	v_mfma_f32_16x16x32_bf16 v[90:93], v[138:141], v[146:149], v[90:93]
	v_mfma_f32_16x16x32_bf16 v[86:89], v[130:133], v[154:157], v[86:89]
	v_mfma_f32_16x16x32_bf16 v[82:85], v[138:141], v[154:157], v[82:85]
	v_mfma_f32_16x16x32_bf16 v[78:81], v[130:133], v[162:165], v[78:81]
	v_mfma_f32_16x16x32_bf16 v[74:77], v[138:141], v[162:165], v[74:77]
	v_mfma_f32_16x16x32_bf16 v[70:73], v[130:133], v[170:173], v[70:73]
	v_mfma_f32_16x16x32_bf16 v[66:69], v[138:141], v[170:173], v[66:69]
	v_mfma_f32_16x16x32_bf16 v[94:97], v[134:137], v[150:153], v[94:97]
	v_mfma_f32_16x16x32_bf16 v[90:93], v[142:145], v[150:153], v[90:93]
	v_mfma_f32_16x16x32_bf16 v[86:89], v[134:137], v[158:161], v[86:89]
	v_mfma_f32_16x16x32_bf16 v[82:85], v[142:145], v[158:161], v[82:85]
	v_mfma_f32_16x16x32_bf16 v[78:81], v[134:137], v[166:169], v[78:81]
	v_mfma_f32_16x16x32_bf16 v[74:77], v[142:145], v[166:169], v[74:77]
	v_mfma_f32_16x16x32_bf16 v[70:73], v[134:137], v[174:177], v[70:73]
	v_mfma_f32_16x16x32_bf16 v[66:69], v[142:145], v[174:177], v[66:69]
	s_setprio 0
	s_mov_b32 m0, s61
	v_lshl_add_u64 v[220:221], s[38:39], 0, v[178:179]
	s_barrier
	ds_read_b128 v[170:173], v215 offset:49152
	ds_read_b128 v[174:177], v215 offset:50176
	ds_read_b128 v[162:165], v215 offset:51200
	ds_read_b128 v[166:169], v215 offset:52224
	ds_read_b128 v[154:157], v215 offset:53248
	ds_read_b128 v[158:161], v215 offset:54272
	ds_read_b128 v[146:149], v215 offset:55296
	ds_read_b128 v[150:153], v215 offset:56320
	global_load_lds_dwordx4 v[220:221], off
	v_lshl_add_u64 v[220:221], s[38:39], 0, v[182:183]
	s_mov_b32 m0, s58
	s_nop 0
	global_load_lds_dwordx4 v[220:221], off
	s_barrier
	s_waitcnt lgkmcnt(0)
	s_setprio 1
	s_waitcnt lgkmcnt(0)
	v_mfma_f32_16x16x32_bf16 v[62:65], v[196:199], v[170:173], v[62:65]
	v_mfma_f32_16x16x32_bf16 v[58:61], v[232:235], v[170:173], v[58:61]
	v_mfma_f32_16x16x32_bf16 v[54:57], v[196:199], v[162:165], v[54:57]
	v_mfma_f32_16x16x32_bf16 v[50:53], v[232:235], v[162:165], v[50:53]
	v_mfma_f32_16x16x32_bf16 v[46:49], v[196:199], v[154:157], v[46:49]
	v_mfma_f32_16x16x32_bf16 v[42:45], v[232:235], v[154:157], v[42:45]
	v_mfma_f32_16x16x32_bf16 v[38:41], v[196:199], v[146:149], v[38:41]
	v_mfma_f32_16x16x32_bf16 v[34:37], v[232:235], v[146:149], v[34:37]
	v_mfma_f32_16x16x32_bf16 v[62:65], v[216:219], v[174:177], v[62:65]
	v_mfma_f32_16x16x32_bf16 v[58:61], v[244:247], v[174:177], v[58:61]
	v_mfma_f32_16x16x32_bf16 v[54:57], v[216:219], v[166:169], v[54:57]
	v_mfma_f32_16x16x32_bf16 v[50:53], v[244:247], v[166:169], v[50:53]
	v_mfma_f32_16x16x32_bf16 v[46:49], v[216:219], v[158:161], v[46:49]
	v_mfma_f32_16x16x32_bf16 v[42:45], v[244:247], v[158:161], v[42:45]
	v_mfma_f32_16x16x32_bf16 v[38:41], v[216:219], v[150:153], v[38:41]
	v_mfma_f32_16x16x32_bf16 v[34:37], v[244:247], v[150:153], v[34:37]
	s_setprio 0
	s_barrier
	s_cmp_lg_u32 s7, 0
	s_cbranch_scc1 .LBB0_919
	v_or_b32_e32 v0, s7, v202
	v_cmp_eq_u32_e64 s[38:39], 0, v0
	s_and_saveexec_b64 s[76:77], s[38:39]
	s_cbranch_execz .LBB0_919
	v_cmp_lt_i32_e32 vcc, 0x20f, v203
	v_add_u32_e32 v0, s90, v203
	s_and_saveexec_b64 s[78:79], vcc
	s_cbranch_execz .LBB0_918
	v_mov_b64_e32 v[196:197], s[40:41]
	s_waitcnt vmcnt(0)
	flat_atomic_add v0, v[196:197], v224 sc0
	s_movk_i32 s0, 0x20f
	s_waitcnt vmcnt(0) lgkmcnt(0)
	v_cmp_lt_i32_e64 s[38:39], s0, v0
	v_add_u32_e32 v0, s63, v0
	s_and_saveexec_b64 s[0:1], s[38:39]
	s_cbranch_execz .LBB0_917
	v_mov_b64_e32 v[196:197], s[42:43]
	flat_atomic_add v0, v[196:197], v224 sc0
	s_movk_i32 s8, 0x20f
	s_waitcnt vmcnt(0) lgkmcnt(0)
	v_cmp_lt_i32_e64 s[38:39], s8, v0
	v_add_u32_e32 v0, s2, v0
	s_and_saveexec_b64 s[80:81], s[38:39]
	s_cbranch_execz .LBB0_916
	v_mov_b64_e32 v[196:197], s[44:45]
	flat_atomic_add v0, v[196:197], v224 sc0
	s_waitcnt vmcnt(0) lgkmcnt(0)
	v_cmp_lt_i32_e64 s[38:39], s8, v0
	v_add_u32_e32 v0, s3, v0
	s_and_saveexec_b64 s[82:83], s[38:39]
	s_cbranch_execz .LBB0_915
	v_mov_b64_e32 v[196:197], s[50:51]
	flat_atomic_add v0, v[196:197], v224 sc0
	s_waitcnt vmcnt(0) lgkmcnt(0)
	v_cmp_lt_i32_e64 s[38:39], s8, v0
	v_add_u32_e32 v0, s95, v0
	s_and_saveexec_b64 s[84:85], s[38:39]
	s_cbranch_execz .LBB0_914
	v_mov_b64_e32 v[196:197], s[54:55]
	flat_atomic_add v0, v[196:197], v224 sc0
	s_waitcnt vmcnt(0) lgkmcnt(0)
	v_cmp_lt_i32_e64 s[38:39], s8, v0
	v_add_u32_e32 v0, s28, v0
	s_and_saveexec_b64 s[86:87], s[38:39]
	s_cbranch_execz .LBB0_913
	v_readlane_b32 s8, v254, 54
	v_readlane_b32 s9, v254, 55
	s_nop 1
	v_mov_b64_e32 v[196:197], s[8:9]
	flat_atomic_add v0, v[196:197], v224 sc0
	s_movk_i32 s8, 0x20f
	s_waitcnt vmcnt(0) lgkmcnt(0)
	v_cmp_lt_i32_e64 s[38:39], s8, v0
	v_readlane_b32 s8, v254, 39
	s_nop 1
	v_add_u32_e32 v0, s8, v0
	s_and_saveexec_b64 s[88:89], s[38:39]
	s_cbranch_execz .LBB0_912
	v_readlane_b32 s8, v254, 56
	v_readlane_b32 s9, v254, 57
	s_nop 1
	v_mov_b64_e32 v[196:197], s[8:9]
	flat_atomic_add v0, v[196:197], v224 sc0
	v_readlane_b32 s8, v254, 43
	s_waitcnt vmcnt(0) lgkmcnt(0)
	v_cmp_gt_i32_e64 s[38:39], s91, v0
	v_add_u32_e32 v191, s8, v0
	s_nop 0
	v_cndmask_b32_e64 v0, -1, v191, s[38:39]
	s_branch .LBB0_912
